# GEMM f32 residual epilogues (4 phases) regenerated as pipelined load/compute/store streams with counted vmcnt (3-4 row groups in flight)
# speedup vs baseline: 1.0094x; 1.0094x over previous
;     __device__ __forceinline__ void operator()(const f32x4 (&acc)[2][2][4][2], const Unit& u, int wr, int wc, int fr, int fq) const {
;         const int row0 = u.pm * BM + wr * 64 + fr; const int col0 = u.pn * BM + wc * 32 + 8 * fq;
; #pragma unroll
;         for (int ai = 0; ai < 2; ++ai)
; #pragma unroll
;             for (int m = 0; m < 4; ++m) { const size_t off = (size_t)(row0 + ai * HALF + m * 16) * ldc + col0;
; #pragma unroll
;                 for (int bj = 0; bj < 2; ++bj) { const size_t p = off + bj * HALF;
;                     const f32x4 r0 = *(const f32x4*)(res + p), r1 = *(const f32x4*)(res + p + 4);
;                     *(f32x4*)(out + p) = r0 * alpha + acc[ai][bj][m][0]; *(f32x4*)(out + p + 4) = r1 * alpha + acc[ai][bj][m][1]; } }
;     }
.LBB0_611:
	v_lshl_add_u32 v162, s42, 8, v145
	v_lshl_or_b32 v164, s58, 8, v150
	v_ashrrev_i32_e32 v163, 31, v162
	v_ashrrev_i32_e32 v165, 31, v164
	v_lshlrev_b64 v[148:149], 11, v[162:163]
	v_lshl_add_u64 v[148:149], v[148:149], 0, v[164:165]
	v_readlane_b32 s60, v231, 2
	v_lshlrev_b64 v[148:149], 2, v[148:149]
	v_readlane_b32 s61, v231, 3
	v_lshl_add_u64 v[168:169], s[20:21], 0, v[148:149]
	s_andn2_b64 vcc, exec, s[0:1]
	v_lshl_add_u64 v[166:167], s[60:61], 0, v[148:149]
	v_mov_b64_e32 v[216:217], v[166:167]
	v_mov_b64_e32 v[218:219], v[168:169]
	s_mov_b64 s[98:99], 0x20000
	s_mov_b64 s[100:101], 0xa0000
	global_load_dwordx4 v[232:235], v[216:217], off
	global_load_dwordx4 v[236:239], v[216:217], off offset:16
	global_load_dwordx4 v[240:243], v[216:217], off offset:512
	global_load_dwordx4 v[244:247], v[216:217], off offset:528
	v_lshl_add_u64 v[216:217], v[216:217], 0, s[98:99]
	global_load_dwordx4 v[248:251], v[216:217], off
	global_load_dwordx4 v[252:255], v[216:217], off offset:16
	global_load_dwordx4 v[154:157], v[216:217], off offset:512
	global_load_dwordx4 v[158:161], v[216:217], off offset:528
	v_lshl_add_u64 v[216:217], v[216:217], 0, s[98:99]
	s_mov_b64 s[0:1], -1
	v_readlane_b32 s62, v231, 4
	v_readlane_b32 s63, v231, 5
	v_readlane_b32 s64, v231, 6
	v_readlane_b32 s65, v231, 7
	v_readlane_b32 s66, v231, 8
	v_readlane_b32 s67, v231, 9
	v_readlane_b32 s68, v231, 10
	v_readlane_b32 s69, v231, 11
	v_readlane_b32 s70, v231, 12
	v_readlane_b32 s71, v231, 13
	v_readlane_b32 s72, v231, 14
	v_readlane_b32 s73, v231, 15
	v_readlane_b32 s74, v231, 16
	v_readlane_b32 s75, v231, 17
	s_waitcnt vmcnt(7)
	v_pk_fma_f32 v[124:125], v[232:233], s[12:13], v[124:125] op_sel_hi:[1,0,1]
	v_pk_fma_f32 v[126:127], v[234:235], s[12:13], v[126:127] op_sel_hi:[1,0,1]
	s_waitcnt vmcnt(6)
	v_pk_fma_f32 v[120:121], v[236:237], s[12:13], v[120:121] op_sel_hi:[1,0,1]
	v_pk_fma_f32 v[122:123], v[238:239], s[12:13], v[122:123] op_sel_hi:[1,0,1]
	global_store_dwordx4 v[218:219], v[124:127], off
	global_store_dwordx4 v[218:219], v[120:123], off offset:16
	global_load_dwordx4 v[232:235], v[216:217], off
	global_load_dwordx4 v[236:239], v[216:217], off offset:16
	s_waitcnt vmcnt(9)
	v_pk_fma_f32 v[112:113], v[240:241], s[12:13], v[112:113] op_sel_hi:[1,0,1]
	v_pk_fma_f32 v[114:115], v[242:243], s[12:13], v[114:115] op_sel_hi:[1,0,1]
	s_waitcnt vmcnt(8)
	v_pk_fma_f32 v[108:109], v[244:245], s[12:13], v[108:109] op_sel_hi:[1,0,1]
	v_pk_fma_f32 v[110:111], v[246:247], s[12:13], v[110:111] op_sel_hi:[1,0,1]
	global_store_dwordx4 v[218:219], v[112:115], off offset:512
	global_store_dwordx4 v[218:219], v[108:111], off offset:528
	v_lshl_add_u64 v[218:219], v[218:219], 0, s[98:99]
	global_load_dwordx4 v[240:243], v[216:217], off offset:512
	global_load_dwordx4 v[244:247], v[216:217], off offset:528
	v_lshl_add_u64 v[216:217], v[216:217], 0, s[98:99]
	s_waitcnt vmcnt(11)
	v_pk_fma_f32 v[116:117], v[248:249], s[12:13], v[116:117] op_sel_hi:[1,0,1]
	v_pk_fma_f32 v[118:119], v[250:251], s[12:13], v[118:119] op_sel_hi:[1,0,1]
	s_waitcnt vmcnt(10)
	v_pk_fma_f32 v[104:105], v[252:253], s[12:13], v[104:105] op_sel_hi:[1,0,1]
	v_pk_fma_f32 v[106:107], v[254:255], s[12:13], v[106:107] op_sel_hi:[1,0,1]
	global_store_dwordx4 v[218:219], v[116:119], off
	global_store_dwordx4 v[218:219], v[104:107], off offset:16
	global_load_dwordx4 v[248:251], v[216:217], off
	global_load_dwordx4 v[252:255], v[216:217], off offset:16
	s_waitcnt vmcnt(13)
	v_pk_fma_f32 v[96:97], v[154:155], s[12:13], v[96:97] op_sel_hi:[1,0,1]
	v_pk_fma_f32 v[98:99], v[156:157], s[12:13], v[98:99] op_sel_hi:[1,0,1]
	s_waitcnt vmcnt(12)
	v_pk_fma_f32 v[92:93], v[158:159], s[12:13], v[92:93] op_sel_hi:[1,0,1]
	v_pk_fma_f32 v[94:95], v[160:161], s[12:13], v[94:95] op_sel_hi:[1,0,1]
	global_store_dwordx4 v[218:219], v[96:99], off offset:512
	global_store_dwordx4 v[218:219], v[92:95], off offset:528
	v_lshl_add_u64 v[218:219], v[218:219], 0, s[98:99]
	global_load_dwordx4 v[154:157], v[216:217], off offset:512
	global_load_dwordx4 v[158:161], v[216:217], off offset:528
	v_lshl_add_u64 v[216:217], v[216:217], 0, s[100:101]
	s_waitcnt vmcnt(13)
	v_pk_fma_f32 v[100:101], v[232:233], s[12:13], v[100:101] op_sel_hi:[1,0,1]
	v_pk_fma_f32 v[102:103], v[234:235], s[12:13], v[102:103] op_sel_hi:[1,0,1]
	s_waitcnt vmcnt(12)
	v_pk_fma_f32 v[88:89], v[236:237], s[12:13], v[88:89] op_sel_hi:[1,0,1]
	v_pk_fma_f32 v[90:91], v[238:239], s[12:13], v[90:91] op_sel_hi:[1,0,1]
	global_store_dwordx4 v[218:219], v[100:103], off
	global_store_dwordx4 v[218:219], v[88:91], off offset:16
	global_load_dwordx4 v[232:235], v[216:217], off
	global_load_dwordx4 v[236:239], v[216:217], off offset:16
	s_waitcnt vmcnt(13)
	v_pk_fma_f32 v[80:81], v[240:241], s[12:13], v[80:81] op_sel_hi:[1,0,1]
	v_pk_fma_f32 v[82:83], v[242:243], s[12:13], v[82:83] op_sel_hi:[1,0,1]
	s_waitcnt vmcnt(12)
	v_pk_fma_f32 v[76:77], v[244:245], s[12:13], v[76:77] op_sel_hi:[1,0,1]
	v_pk_fma_f32 v[78:79], v[246:247], s[12:13], v[78:79] op_sel_hi:[1,0,1]
	global_store_dwordx4 v[218:219], v[80:83], off offset:512
	global_store_dwordx4 v[218:219], v[76:79], off offset:528
	v_lshl_add_u64 v[218:219], v[218:219], 0, s[98:99]
	global_load_dwordx4 v[240:243], v[216:217], off offset:512
	global_load_dwordx4 v[244:247], v[216:217], off offset:528
	v_lshl_add_u64 v[216:217], v[216:217], 0, s[98:99]
	s_waitcnt vmcnt(13)
	v_pk_fma_f32 v[84:85], v[248:249], s[12:13], v[84:85] op_sel_hi:[1,0,1]
	v_pk_fma_f32 v[86:87], v[250:251], s[12:13], v[86:87] op_sel_hi:[1,0,1]
	s_waitcnt vmcnt(12)
;     __device__ __forceinline__ void operator()(const f32x4 (&acc)[2][2][4][2], const Unit& u, int wr, int wc, int fr, int fq) const {
;         const int row0 = u.pm * BM + wr * 64 + fr; const int col0 = u.pn * BM + wc * 32 + 8 * fq;
; #pragma unroll
;         for (int ai = 0; ai < 2; ++ai)
; #pragma unroll
;             for (int m = 0; m < 4; ++m) { const size_t off = (size_t)(row0 + ai * HALF + m * 16) * ldc + col0;
; #pragma unroll
;                 for (int bj = 0; bj < 2; ++bj) { const size_t p = off + bj * HALF;
;                     const f32x4 r0 = *(const f32x4*)(res + p), r1 = *(const f32x4*)(res + p + 4);
;                     *(f32x4*)(out + p) = r0 * alpha + acc[ai][bj][m][0]; *(f32x4*)(out + p + 4) = r1 * alpha + acc[ai][bj][m][1]; } }
;     }
	v_pk_fma_f32 v[72:73], v[252:253], s[12:13], v[72:73] op_sel_hi:[1,0,1]
	v_pk_fma_f32 v[74:75], v[254:255], s[12:13], v[74:75] op_sel_hi:[1,0,1]
	global_store_dwordx4 v[218:219], v[84:87], off
	global_store_dwordx4 v[218:219], v[72:75], off offset:16
	global_load_dwordx4 v[248:251], v[216:217], off
	global_load_dwordx4 v[252:255], v[216:217], off offset:16
	s_waitcnt vmcnt(13)
	v_pk_fma_f32 v[68:69], v[154:155], s[12:13], v[68:69] op_sel_hi:[1,0,1]
	v_pk_fma_f32 v[70:71], v[156:157], s[12:13], v[70:71] op_sel_hi:[1,0,1]
	s_waitcnt vmcnt(12)
	v_pk_fma_f32 v[64:65], v[158:159], s[12:13], v[64:65] op_sel_hi:[1,0,1]
	v_pk_fma_f32 v[66:67], v[160:161], s[12:13], v[66:67] op_sel_hi:[1,0,1]
	global_store_dwordx4 v[218:219], v[68:71], off offset:512
	global_store_dwordx4 v[218:219], v[64:67], off offset:528
	v_lshl_add_u64 v[218:219], v[218:219], 0, s[100:101]
	global_load_dwordx4 v[154:157], v[216:217], off offset:512
	global_load_dwordx4 v[158:161], v[216:217], off offset:528
	v_lshl_add_u64 v[216:217], v[216:217], 0, s[98:99]
	s_waitcnt vmcnt(13)
	v_pk_fma_f32 v[60:61], v[232:233], s[12:13], v[60:61] op_sel_hi:[1,0,1]
	v_pk_fma_f32 v[62:63], v[234:235], s[12:13], v[62:63] op_sel_hi:[1,0,1]
	s_waitcnt vmcnt(12)
	v_pk_fma_f32 v[56:57], v[236:237], s[12:13], v[56:57] op_sel_hi:[1,0,1]
	v_pk_fma_f32 v[58:59], v[238:239], s[12:13], v[58:59] op_sel_hi:[1,0,1]
	global_store_dwordx4 v[218:219], v[60:63], off
	global_store_dwordx4 v[218:219], v[56:59], off offset:16
	global_load_dwordx4 v[232:235], v[216:217], off
	global_load_dwordx4 v[236:239], v[216:217], off offset:16
	s_waitcnt vmcnt(13)
	v_pk_fma_f32 v[48:49], v[240:241], s[12:13], v[48:49] op_sel_hi:[1,0,1]
	v_pk_fma_f32 v[50:51], v[242:243], s[12:13], v[50:51] op_sel_hi:[1,0,1]
	s_waitcnt vmcnt(12)
	v_pk_fma_f32 v[44:45], v[244:245], s[12:13], v[44:45] op_sel_hi:[1,0,1]
	v_pk_fma_f32 v[46:47], v[246:247], s[12:13], v[46:47] op_sel_hi:[1,0,1]
	global_store_dwordx4 v[218:219], v[48:51], off offset:512
	global_store_dwordx4 v[218:219], v[44:47], off offset:528
	v_lshl_add_u64 v[218:219], v[218:219], 0, s[98:99]
	global_load_dwordx4 v[240:243], v[216:217], off offset:512
	global_load_dwordx4 v[244:247], v[216:217], off offset:528
	v_lshl_add_u64 v[216:217], v[216:217], 0, s[98:99]
	s_waitcnt vmcnt(13)
	v_pk_fma_f32 v[52:53], v[248:249], s[12:13], v[52:53] op_sel_hi:[1,0,1]
	v_pk_fma_f32 v[54:55], v[250:251], s[12:13], v[54:55] op_sel_hi:[1,0,1]
	s_waitcnt vmcnt(12)
	v_pk_fma_f32 v[40:41], v[252:253], s[12:13], v[40:41] op_sel_hi:[1,0,1]
	v_pk_fma_f32 v[42:43], v[254:255], s[12:13], v[42:43] op_sel_hi:[1,0,1]
	global_store_dwordx4 v[218:219], v[52:55], off
	global_store_dwordx4 v[218:219], v[40:43], off offset:16
	global_load_dwordx4 v[248:251], v[216:217], off
	global_load_dwordx4 v[252:255], v[216:217], off offset:16
	s_waitcnt vmcnt(13)
	v_pk_fma_f32 v[32:33], v[154:155], s[12:13], v[32:33] op_sel_hi:[1,0,1]
	v_pk_fma_f32 v[34:35], v[156:157], s[12:13], v[34:35] op_sel_hi:[1,0,1]
	s_waitcnt vmcnt(12)
	v_pk_fma_f32 v[28:29], v[158:159], s[12:13], v[28:29] op_sel_hi:[1,0,1]
	v_pk_fma_f32 v[30:31], v[160:161], s[12:13], v[30:31] op_sel_hi:[1,0,1]
	global_store_dwordx4 v[218:219], v[32:35], off offset:512
	global_store_dwordx4 v[218:219], v[28:31], off offset:528
	v_lshl_add_u64 v[218:219], v[218:219], 0, s[98:99]
	global_load_dwordx4 v[154:157], v[216:217], off offset:512
	global_load_dwordx4 v[158:161], v[216:217], off offset:528
	v_lshl_add_u64 v[216:217], v[216:217], 0, s[98:99]
	s_waitcnt vmcnt(13)
	v_pk_fma_f32 v[36:37], v[232:233], s[12:13], v[36:37] op_sel_hi:[1,0,1]
	v_pk_fma_f32 v[38:39], v[234:235], s[12:13], v[38:39] op_sel_hi:[1,0,1]
	s_waitcnt vmcnt(12)
	v_pk_fma_f32 v[24:25], v[236:237], s[12:13], v[24:25] op_sel_hi:[1,0,1]
	v_pk_fma_f32 v[26:27], v[238:239], s[12:13], v[26:27] op_sel_hi:[1,0,1]
	global_store_dwordx4 v[218:219], v[36:39], off
	global_store_dwordx4 v[218:219], v[24:27], off offset:16
	s_waitcnt vmcnt(11)
	v_pk_fma_f32 v[16:17], v[240:241], s[12:13], v[16:17] op_sel_hi:[1,0,1]
	v_pk_fma_f32 v[18:19], v[242:243], s[12:13], v[18:19] op_sel_hi:[1,0,1]
	s_waitcnt vmcnt(10)
	v_pk_fma_f32 v[12:13], v[244:245], s[12:13], v[12:13] op_sel_hi:[1,0,1]
	v_pk_fma_f32 v[14:15], v[246:247], s[12:13], v[14:15] op_sel_hi:[1,0,1]
	global_store_dwordx4 v[218:219], v[16:19], off offset:512
	global_store_dwordx4 v[218:219], v[12:15], off offset:528
	v_lshl_add_u64 v[218:219], v[218:219], 0, s[98:99]
	s_waitcnt vmcnt(9)
	v_pk_fma_f32 v[20:21], v[248:249], s[12:13], v[20:21] op_sel_hi:[1,0,1]
	v_pk_fma_f32 v[22:23], v[250:251], s[12:13], v[22:23] op_sel_hi:[1,0,1]
	s_waitcnt vmcnt(8)
	v_pk_fma_f32 v[8:9], v[252:253], s[12:13], v[8:9] op_sel_hi:[1,0,1]
	v_pk_fma_f32 v[10:11], v[254:255], s[12:13], v[10:11] op_sel_hi:[1,0,1]
	global_store_dwordx4 v[218:219], v[20:23], off
	global_store_dwordx4 v[218:219], v[8:11], off offset:16
	s_waitcnt vmcnt(7)
	v_pk_fma_f32 v[4:5], v[154:155], s[12:13], v[4:5] op_sel_hi:[1,0,1]
	v_pk_fma_f32 v[6:7], v[156:157], s[12:13], v[6:7] op_sel_hi:[1,0,1]
	s_waitcnt vmcnt(6)
	v_pk_fma_f32 v[0:1], v[158:159], s[12:13], v[0:1] op_sel_hi:[1,0,1]
	v_pk_fma_f32 v[2:3], v[160:161], s[12:13], v[2:3] op_sel_hi:[1,0,1]
	global_store_dwordx4 v[218:219], v[4:7], off offset:512
	global_store_dwordx4 v[218:219], v[0:3], off offset:528
	v_lshl_add_u64 v[218:219], v[218:219], 0, s[98:99]
	s_cbranch_vccnz .LBB0_600
	s_andn2_b64 vcc, exec, s[6:7]
	s_cbranch_vccnz .LBB0_599
	s_barrier
	s_branch .LBB0_599

;     __device__ __forceinline__ void operator()(const f32x4 (&acc)[2][2][4][2], const Unit& u, int wr, int wc, int fr, int fq) const {
;         const int row0 = u.pm * BM + wr * 64 + fr; const int col0 = u.pn * BM + wc * 32 + 8 * fq;
; #pragma unroll
;         for (int bj = 0; bj < 2; ++bj) {
;             const f32x4 g0 = *(const f32x4*)(g + col0 + bj * HALF), g1 = *(const f32x4*)(g + col0 + bj * HALF + 4);
;             const f32x4 b0 = *(const f32x4*)(b + col0 + bj * HALF), b1 = *(const f32x4*)(b + col0 + bj * HALF + 4);
; #pragma unroll
;             for (int ai = 0; ai < 2; ++ai)
; #pragma unroll
;                 for (int m = 0; m < 4; ++m) { const int row = row0 + ai * HALF + m * 16; const size_t p = (size_t)row * ldc + col0 + bj * HALF;
;                     const float mean = stats[2 * row], rstd = stats[2 * row + 1];
;                     const f32x4 r0 = *(const f32x4*)(res + p), r1 = *(const f32x4*)(res + p + 4);
;                     const f32x4 n0 = (r0 - mean) * rstd * g0 + b0, n1 = (r1 - mean) * rstd * g1 + b1;
;                     *(f32x4*)(out + p) = n0 * alpha + acc[ai][bj][m][0]; *(f32x4*)(out + p + 4) = n1 * alpha + acc[ai][bj][m][1]; }
;         }
;     }
.LBB0_811:
	v_lshl_or_b32 v128, s52, 8, v180
	v_lshl_add_u32 v178, s36, 8, v145
	v_ashrrev_i32_e32 v129, 31, v128
	v_lshlrev_b64 v[176:177], 2, v[128:129]
	v_lshlrev_b32_e32 v128, 1, v178
	v_ashrrev_i32_e32 v179, 31, v178
	v_ashrrev_i32_e32 v129, 31, v128
	v_lshl_add_u64 v[168:169], v[128:129], 2, s[8:9]
	v_lshlrev_b64 v[128:129], 13, v[178:179]
	v_readlane_b32 s52, v231, 2
	v_lshl_add_u64 v[128:129], s[20:21], 0, v[128:129]
	v_readlane_b32 s60, v231, 10
	v_readlane_b32 s61, v231, 11
	v_readlane_b32 s62, v231, 12
	v_readlane_b32 s63, v231, 13
	v_readlane_b32 s64, v231, 14
	v_readlane_b32 s65, v231, 15
	v_lshl_add_u64 v[164:165], v[128:129], 0, v[176:177]
	v_readlane_b32 s66, v231, 16
	v_readlane_b32 s67, v231, 17
	s_mov_b64 s[60:61], s[64:65]
	s_mov_b64 s[62:63], s[66:67]
	v_lshl_add_u64 v[172:173], s[62:63], 0, v[176:177]
	v_lshl_add_u64 v[170:171], s[60:61], 0, v[176:177]
	v_or_b32_e32 v166, 16, v178
	v_ashrrev_i32_e32 v167, 31, v166
	v_lshlrev_b32_e32 v174, 1, v166
	v_ashrrev_i32_e32 v175, 31, v174
	v_lshlrev_b64 v[166:167], 13, v[166:167]
	v_lshl_add_u64 v[174:175], v[174:175], 2, s[8:9]
	v_lshl_add_u64 v[166:167], s[20:21], 0, v[166:167]
	v_lshl_add_u64 v[166:167], v[166:167], 0, v[176:177]
	s_andn2_b64 vcc, exec, s[0:1]
	s_mov_b64 s[0:1], -1
	v_readlane_b32 s53, v231, 3
	v_readlane_b32 s54, v231, 4
	v_readlane_b32 s55, v231, 5
	v_readlane_b32 s56, v231, 6
	v_readlane_b32 s57, v231, 7
	v_readlane_b32 s58, v231, 8
	v_readlane_b32 s59, v231, 9
	v_mov_b64_e32 v[216:217], v[164:165]
	v_mov_b64_e32 v[218:219], v[164:165]
	s_mov_b64 s[98:99], 0x20000
	s_mov_b64 s[100:101], 0xa0000
	v_mov_b32_e32 v220, 0x200
	v_mov_b32_e32 v221, 0
	global_load_dwordx4 v[128:131], v[170:171], off offset:16
	global_load_dwordx4 v[132:135], v[172:173], off
	global_load_dwordx4 v[136:139], v[170:171], off
	global_load_dwordx4 v[140:143], v[172:173], off offset:16
	global_load_dwordx2 v[240:241], v[168:169], off
	global_load_dwordx4 v[232:235], v[216:217], off
	global_load_dwordx4 v[236:239], v[216:217], off offset:16
	v_lshl_add_u64 v[216:217], v[216:217], 0, s[98:99]
	global_load_dwordx2 v[242:243], v[168:169], off offset:128
	global_load_dwordx4 v[244:247], v[216:217], off
	global_load_dwordx4 v[248:251], v[216:217], off offset:16
	v_lshl_add_u64 v[216:217], v[216:217], 0, s[98:99]
	global_load_dwordx2 v[192:193], v[168:169], off offset:256
	global_load_dwordx4 v[184:187], v[216:217], off
	global_load_dwordx4 v[188:191], v[216:217], off offset:16
	v_lshl_add_u64 v[216:217], v[216:217], 0, s[98:99]
	s_waitcnt vmcnt(6)
	v_sub_f32_e32 v232, v232, v240
	v_sub_f32_e32 v233, v233, v240
	v_sub_f32_e32 v234, v234, v240
	v_sub_f32_e32 v235, v235, v240
	v_sub_f32_e32 v236, v236, v240
	v_sub_f32_e32 v237, v237, v240
	v_sub_f32_e32 v238, v238, v240
	v_sub_f32_e32 v239, v239, v240
	v_pk_mul_f32 v[232:233], v[240:241], v[232:233] op_sel:[1,0]
	v_pk_mul_f32 v[234:235], v[240:241], v[234:235] op_sel:[1,0]
	v_pk_mul_f32 v[236:237], v[240:241], v[236:237] op_sel:[1,0]
	v_pk_mul_f32 v[238:239], v[240:241], v[238:239] op_sel:[1,0]
	v_pk_fma_f32 v[232:233], v[136:137], v[232:233], v[132:133]
	v_pk_fma_f32 v[234:235], v[138:139], v[234:235], v[134:135]
	v_pk_fma_f32 v[236:237], v[128:129], v[236:237], v[140:141]
	v_pk_fma_f32 v[238:239], v[130:131], v[238:239], v[142:143]
	v_pk_fma_f32 v[124:125], v[232:233], s[14:15], v[124:125] op_sel_hi:[1,0,1]
	v_pk_fma_f32 v[126:127], v[234:235], s[14:15], v[126:127] op_sel_hi:[1,0,1]
	v_pk_fma_f32 v[120:121], v[236:237], s[14:15], v[120:121] op_sel_hi:[1,0,1]
	v_pk_fma_f32 v[122:123], v[238:239], s[14:15], v[122:123] op_sel_hi:[1,0,1]
	global_store_dwordx4 v[218:219], v[124:127], off
	global_store_dwordx4 v[218:219], v[120:123], off offset:16
	v_lshl_add_u64 v[218:219], v[218:219], 0, s[98:99]
	global_load_dwordx2 v[240:241], v[168:169], off offset:384
	global_load_dwordx4 v[232:235], v[216:217], off
	global_load_dwordx4 v[236:239], v[216:217], off offset:16
	v_lshl_add_u64 v[216:217], v[216:217], 0, s[100:101]
	s_waitcnt vmcnt(8)
	v_sub_f32_e32 v244, v244, v242
	v_sub_f32_e32 v245, v245, v242
	v_sub_f32_e32 v246, v246, v242
	v_sub_f32_e32 v247, v247, v242
	v_sub_f32_e32 v248, v248, v242
	v_sub_f32_e32 v249, v249, v242
	v_sub_f32_e32 v250, v250, v242
	v_sub_f32_e32 v251, v251, v242
	v_pk_mul_f32 v[244:245], v[242:243], v[244:245] op_sel:[1,0]
	v_pk_mul_f32 v[246:247], v[242:243], v[246:247] op_sel:[1,0]
	v_pk_mul_f32 v[248:249], v[242:243], v[248:249] op_sel:[1,0]
	v_pk_mul_f32 v[250:251], v[242:243], v[250:251] op_sel:[1,0]
	v_pk_fma_f32 v[244:245], v[136:137], v[244:245], v[132:133]
	v_pk_fma_f32 v[246:247], v[138:139], v[246:247], v[134:135]
	v_pk_fma_f32 v[248:249], v[128:129], v[248:249], v[140:141]
	v_pk_fma_f32 v[250:251], v[130:131], v[250:251], v[142:143]
	v_pk_fma_f32 v[116:117], v[244:245], s[14:15], v[116:117] op_sel_hi:[1,0,1]
	v_pk_fma_f32 v[118:119], v[246:247], s[14:15], v[118:119] op_sel_hi:[1,0,1]
	v_pk_fma_f32 v[112:113], v[248:249], s[14:15], v[112:113] op_sel_hi:[1,0,1]
	v_pk_fma_f32 v[114:115], v[250:251], s[14:15], v[114:115] op_sel_hi:[1,0,1]
	global_store_dwordx4 v[218:219], v[116:119], off
	global_store_dwordx4 v[218:219], v[112:115], off offset:16
	v_lshl_add_u64 v[218:219], v[218:219], 0, s[98:99]
	global_load_dwordx2 v[242:243], v[168:169], off offset:1024
	global_load_dwordx4 v[244:247], v[216:217], off
	global_load_dwordx4 v[248:251], v[216:217], off offset:16
	v_lshl_add_u64 v[216:217], v[216:217], 0, s[98:99]
	s_waitcnt vmcnt(10)
;     __device__ __forceinline__ void operator()(const f32x4 (&acc)[2][2][4][2], const Unit& u, int wr, int wc, int fr, int fq) const {
;         const int row0 = u.pm * BM + wr * 64 + fr; const int col0 = u.pn * BM + wc * 32 + 8 * fq;
; #pragma unroll
;         for (int bj = 0; bj < 2; ++bj) {
;             const f32x4 g0 = *(const f32x4*)(g + col0 + bj * HALF), g1 = *(const f32x4*)(g + col0 + bj * HALF + 4);
;             const f32x4 b0 = *(const f32x4*)(b + col0 + bj * HALF), b1 = *(const f32x4*)(b + col0 + bj * HALF + 4);
; #pragma unroll
;             for (int ai = 0; ai < 2; ++ai)
; #pragma unroll
;                 for (int m = 0; m < 4; ++m) { const int row = row0 + ai * HALF + m * 16; const size_t p = (size_t)row * ldc + col0 + bj * HALF;
;                     const float mean = stats[2 * row], rstd = stats[2 * row + 1];
;                     const f32x4 r0 = *(const f32x4*)(res + p), r1 = *(const f32x4*)(res + p + 4);
;                     const f32x4 n0 = (r0 - mean) * rstd * g0 + b0, n1 = (r1 - mean) * rstd * g1 + b1;
;                     *(f32x4*)(out + p) = n0 * alpha + acc[ai][bj][m][0]; *(f32x4*)(out + p + 4) = n1 * alpha + acc[ai][bj][m][1]; }
;         }
;     }
	v_sub_f32_e32 v184, v184, v192
	v_sub_f32_e32 v185, v185, v192
	v_sub_f32_e32 v186, v186, v192
	v_sub_f32_e32 v187, v187, v192
	v_sub_f32_e32 v188, v188, v192
	v_sub_f32_e32 v189, v189, v192
	v_sub_f32_e32 v190, v190, v192
	v_sub_f32_e32 v191, v191, v192
	v_pk_mul_f32 v[184:185], v[192:193], v[184:185] op_sel:[1,0]
	v_pk_mul_f32 v[186:187], v[192:193], v[186:187] op_sel:[1,0]
	v_pk_mul_f32 v[188:189], v[192:193], v[188:189] op_sel:[1,0]
	v_pk_mul_f32 v[190:191], v[192:193], v[190:191] op_sel:[1,0]
	v_pk_fma_f32 v[184:185], v[136:137], v[184:185], v[132:133]
	v_pk_fma_f32 v[186:187], v[138:139], v[186:187], v[134:135]
	v_pk_fma_f32 v[188:189], v[128:129], v[188:189], v[140:141]
	v_pk_fma_f32 v[190:191], v[130:131], v[190:191], v[142:143]
	v_pk_fma_f32 v[108:109], v[184:185], s[14:15], v[108:109] op_sel_hi:[1,0,1]
	v_pk_fma_f32 v[110:111], v[186:187], s[14:15], v[110:111] op_sel_hi:[1,0,1]
	v_pk_fma_f32 v[104:105], v[188:189], s[14:15], v[104:105] op_sel_hi:[1,0,1]
	v_pk_fma_f32 v[106:107], v[190:191], s[14:15], v[106:107] op_sel_hi:[1,0,1]
	global_store_dwordx4 v[218:219], v[108:111], off
	global_store_dwordx4 v[218:219], v[104:107], off offset:16
	v_lshl_add_u64 v[218:219], v[218:219], 0, s[98:99]
	global_load_dwordx2 v[192:193], v[168:169], off offset:1152
	global_load_dwordx4 v[184:187], v[216:217], off
	global_load_dwordx4 v[188:191], v[216:217], off offset:16
	v_lshl_add_u64 v[216:217], v[216:217], 0, s[98:99]
	s_waitcnt vmcnt(10)
	v_sub_f32_e32 v232, v232, v240
	v_sub_f32_e32 v233, v233, v240
	v_sub_f32_e32 v234, v234, v240
	v_sub_f32_e32 v235, v235, v240
	v_sub_f32_e32 v236, v236, v240
	v_sub_f32_e32 v237, v237, v240
	v_sub_f32_e32 v238, v238, v240
	v_sub_f32_e32 v239, v239, v240
	v_pk_mul_f32 v[232:233], v[240:241], v[232:233] op_sel:[1,0]
	v_pk_mul_f32 v[234:235], v[240:241], v[234:235] op_sel:[1,0]
	v_pk_mul_f32 v[236:237], v[240:241], v[236:237] op_sel:[1,0]
	v_pk_mul_f32 v[238:239], v[240:241], v[238:239] op_sel:[1,0]
	v_pk_fma_f32 v[232:233], v[136:137], v[232:233], v[132:133]
	v_pk_fma_f32 v[234:235], v[138:139], v[234:235], v[134:135]
	v_pk_fma_f32 v[236:237], v[128:129], v[236:237], v[140:141]
	v_pk_fma_f32 v[238:239], v[130:131], v[238:239], v[142:143]
	v_pk_fma_f32 v[100:101], v[232:233], s[14:15], v[100:101] op_sel_hi:[1,0,1]
	v_pk_fma_f32 v[102:103], v[234:235], s[14:15], v[102:103] op_sel_hi:[1,0,1]
	v_pk_fma_f32 v[96:97], v[236:237], s[14:15], v[96:97] op_sel_hi:[1,0,1]
	v_pk_fma_f32 v[98:99], v[238:239], s[14:15], v[98:99] op_sel_hi:[1,0,1]
	global_store_dwordx4 v[218:219], v[100:103], off
	global_store_dwordx4 v[218:219], v[96:99], off offset:16
	v_lshl_add_u64 v[218:219], v[218:219], 0, s[100:101]
	global_load_dwordx2 v[240:241], v[168:169], off offset:1280
	global_load_dwordx4 v[232:235], v[216:217], off
	global_load_dwordx4 v[236:239], v[216:217], off offset:16
	v_lshl_add_u64 v[216:217], v[216:217], 0, s[98:99]
	s_waitcnt vmcnt(10)
	v_sub_f32_e32 v244, v244, v242
	v_sub_f32_e32 v245, v245, v242
	v_sub_f32_e32 v246, v246, v242
	v_sub_f32_e32 v247, v247, v242
	v_sub_f32_e32 v248, v248, v242
	v_sub_f32_e32 v249, v249, v242
	v_sub_f32_e32 v250, v250, v242
	v_sub_f32_e32 v251, v251, v242
	v_pk_mul_f32 v[244:245], v[242:243], v[244:245] op_sel:[1,0]
	v_pk_mul_f32 v[246:247], v[242:243], v[246:247] op_sel:[1,0]
	v_pk_mul_f32 v[248:249], v[242:243], v[248:249] op_sel:[1,0]
	v_pk_mul_f32 v[250:251], v[242:243], v[250:251] op_sel:[1,0]
	v_pk_fma_f32 v[244:245], v[136:137], v[244:245], v[132:133]
	v_pk_fma_f32 v[246:247], v[138:139], v[246:247], v[134:135]
	v_pk_fma_f32 v[248:249], v[128:129], v[248:249], v[140:141]
	v_pk_fma_f32 v[250:251], v[130:131], v[250:251], v[142:143]
	v_pk_fma_f32 v[92:93], v[244:245], s[14:15], v[92:93] op_sel_hi:[1,0,1]
	v_pk_fma_f32 v[94:95], v[246:247], s[14:15], v[94:95] op_sel_hi:[1,0,1]
	v_pk_fma_f32 v[88:89], v[248:249], s[14:15], v[88:89] op_sel_hi:[1,0,1]
	v_pk_fma_f32 v[90:91], v[250:251], s[14:15], v[90:91] op_sel_hi:[1,0,1]
	global_store_dwordx4 v[218:219], v[92:95], off
	global_store_dwordx4 v[218:219], v[88:91], off offset:16
	v_lshl_add_u64 v[218:219], v[218:219], 0, s[98:99]
	global_load_dwordx2 v[242:243], v[168:169], off offset:1408
	global_load_dwordx4 v[244:247], v[216:217], off
	global_load_dwordx4 v[248:251], v[216:217], off offset:16
	v_lshl_add_u64 v[216:217], v[220:221], 0, v[164:165]
	s_waitcnt vmcnt(10)
	v_sub_f32_e32 v184, v184, v192
	v_sub_f32_e32 v185, v185, v192
	v_sub_f32_e32 v186, v186, v192
	v_sub_f32_e32 v187, v187, v192
	v_sub_f32_e32 v188, v188, v192
	v_sub_f32_e32 v189, v189, v192
	v_sub_f32_e32 v190, v190, v192
	v_sub_f32_e32 v191, v191, v192
	v_pk_mul_f32 v[184:185], v[192:193], v[184:185] op_sel:[1,0]
	v_pk_mul_f32 v[186:187], v[192:193], v[186:187] op_sel:[1,0]
	v_pk_mul_f32 v[188:189], v[192:193], v[188:189] op_sel:[1,0]
	v_pk_mul_f32 v[190:191], v[192:193], v[190:191] op_sel:[1,0]
	v_pk_fma_f32 v[184:185], v[136:137], v[184:185], v[132:133]
	v_pk_fma_f32 v[186:187], v[138:139], v[186:187], v[134:135]
	v_pk_fma_f32 v[188:189], v[128:129], v[188:189], v[140:141]
	v_pk_fma_f32 v[190:191], v[130:131], v[190:191], v[142:143]
	v_pk_fma_f32 v[84:85], v[184:185], s[14:15], v[84:85] op_sel_hi:[1,0,1]
	v_pk_fma_f32 v[86:87], v[186:187], s[14:15], v[86:87] op_sel_hi:[1,0,1]
	v_pk_fma_f32 v[80:81], v[188:189], s[14:15], v[80:81] op_sel_hi:[1,0,1]
	v_pk_fma_f32 v[82:83], v[190:191], s[14:15], v[82:83] op_sel_hi:[1,0,1]
	global_store_dwordx4 v[218:219], v[84:87], off
	global_store_dwordx4 v[218:219], v[80:83], off offset:16
	v_lshl_add_u64 v[218:219], v[218:219], 0, s[98:99]
	global_load_dwordx2 v[192:193], v[168:169], off
	global_load_dwordx4 v[184:187], v[216:217], off
	global_load_dwordx4 v[188:191], v[216:217], off offset:16
	v_lshl_add_u64 v[216:217], v[216:217], 0, s[98:99]
	s_waitcnt vmcnt(10)
;     __device__ __forceinline__ void operator()(const f32x4 (&acc)[2][2][4][2], const Unit& u, int wr, int wc, int fr, int fq) const {
;         const int row0 = u.pm * BM + wr * 64 + fr; const int col0 = u.pn * BM + wc * 32 + 8 * fq;
; #pragma unroll
;         for (int bj = 0; bj < 2; ++bj) {
;             const f32x4 g0 = *(const f32x4*)(g + col0 + bj * HALF), g1 = *(const f32x4*)(g + col0 + bj * HALF + 4);
;             const f32x4 b0 = *(const f32x4*)(b + col0 + bj * HALF), b1 = *(const f32x4*)(b + col0 + bj * HALF + 4);
; #pragma unroll
;             for (int ai = 0; ai < 2; ++ai)
; #pragma unroll
;                 for (int m = 0; m < 4; ++m) { const int row = row0 + ai * HALF + m * 16; const size_t p = (size_t)row * ldc + col0 + bj * HALF;
;                     const float mean = stats[2 * row], rstd = stats[2 * row + 1];
;                     const f32x4 r0 = *(const f32x4*)(res + p), r1 = *(const f32x4*)(res + p + 4);
;                     const f32x4 n0 = (r0 - mean) * rstd * g0 + b0, n1 = (r1 - mean) * rstd * g1 + b1;
;                     *(f32x4*)(out + p) = n0 * alpha + acc[ai][bj][m][0]; *(f32x4*)(out + p + 4) = n1 * alpha + acc[ai][bj][m][1]; }
;         }
;     }
	v_sub_f32_e32 v232, v232, v240
	v_sub_f32_e32 v233, v233, v240
	v_sub_f32_e32 v234, v234, v240
	v_sub_f32_e32 v235, v235, v240
	v_sub_f32_e32 v236, v236, v240
	v_sub_f32_e32 v237, v237, v240
	v_sub_f32_e32 v238, v238, v240
	v_sub_f32_e32 v239, v239, v240
	v_pk_mul_f32 v[232:233], v[240:241], v[232:233] op_sel:[1,0]
	v_pk_mul_f32 v[234:235], v[240:241], v[234:235] op_sel:[1,0]
	v_pk_mul_f32 v[236:237], v[240:241], v[236:237] op_sel:[1,0]
	v_pk_mul_f32 v[238:239], v[240:241], v[238:239] op_sel:[1,0]
	v_pk_fma_f32 v[232:233], v[136:137], v[232:233], v[132:133]
	v_pk_fma_f32 v[234:235], v[138:139], v[234:235], v[134:135]
	v_pk_fma_f32 v[236:237], v[128:129], v[236:237], v[140:141]
	v_pk_fma_f32 v[238:239], v[130:131], v[238:239], v[142:143]
	v_pk_fma_f32 v[76:77], v[232:233], s[14:15], v[76:77] op_sel_hi:[1,0,1]
	v_pk_fma_f32 v[78:79], v[234:235], s[14:15], v[78:79] op_sel_hi:[1,0,1]
	v_pk_fma_f32 v[72:73], v[236:237], s[14:15], v[72:73] op_sel_hi:[1,0,1]
	v_pk_fma_f32 v[74:75], v[238:239], s[14:15], v[74:75] op_sel_hi:[1,0,1]
	global_store_dwordx4 v[218:219], v[76:79], off
	global_store_dwordx4 v[218:219], v[72:75], off offset:16
	v_lshl_add_u64 v[218:219], v[218:219], 0, s[98:99]
	global_load_dwordx2 v[240:241], v[168:169], off offset:128
	global_load_dwordx4 v[232:235], v[216:217], off
	global_load_dwordx4 v[236:239], v[216:217], off offset:16
	v_lshl_add_u64 v[216:217], v[216:217], 0, s[98:99]
	s_waitcnt vmcnt(10)
	v_sub_f32_e32 v244, v244, v242
	v_sub_f32_e32 v245, v245, v242
	v_sub_f32_e32 v246, v246, v242
	v_sub_f32_e32 v247, v247, v242
	v_sub_f32_e32 v248, v248, v242
	v_sub_f32_e32 v249, v249, v242
	v_sub_f32_e32 v250, v250, v242
	v_sub_f32_e32 v251, v251, v242
	v_pk_mul_f32 v[244:245], v[242:243], v[244:245] op_sel:[1,0]
	v_pk_mul_f32 v[246:247], v[242:243], v[246:247] op_sel:[1,0]
	v_pk_mul_f32 v[248:249], v[242:243], v[248:249] op_sel:[1,0]
	v_pk_mul_f32 v[250:251], v[242:243], v[250:251] op_sel:[1,0]
	v_pk_fma_f32 v[244:245], v[136:137], v[244:245], v[132:133]
	v_pk_fma_f32 v[246:247], v[138:139], v[246:247], v[134:135]
	v_pk_fma_f32 v[248:249], v[128:129], v[248:249], v[140:141]
	v_pk_fma_f32 v[250:251], v[130:131], v[250:251], v[142:143]
	v_pk_fma_f32 v[68:69], v[244:245], s[14:15], v[68:69] op_sel_hi:[1,0,1]
	v_pk_fma_f32 v[70:71], v[246:247], s[14:15], v[70:71] op_sel_hi:[1,0,1]
	v_pk_fma_f32 v[60:61], v[248:249], s[14:15], v[60:61] op_sel_hi:[1,0,1]
	v_pk_fma_f32 v[62:63], v[250:251], s[14:15], v[62:63] op_sel_hi:[1,0,1]
	global_store_dwordx4 v[218:219], v[68:71], off
	global_store_dwordx4 v[218:219], v[60:63], off offset:16
	v_lshl_add_u64 v[218:219], v[220:221], 0, v[164:165]
	global_load_dwordx2 v[242:243], v[168:169], off offset:256
	global_load_dwordx4 v[244:247], v[216:217], off
	global_load_dwordx4 v[248:251], v[216:217], off offset:16
	v_lshl_add_u64 v[216:217], v[216:217], 0, s[98:99]
	global_load_dwordx4 v[128:131], v[170:171], off offset:528
	global_load_dwordx4 v[132:135], v[172:173], off offset:512
	global_load_dwordx4 v[136:139], v[170:171], off offset:512
	global_load_dwordx4 v[140:143], v[172:173], off offset:528
	s_waitcnt vmcnt(0)
	v_sub_f32_e32 v184, v184, v192
	v_sub_f32_e32 v185, v185, v192
	v_sub_f32_e32 v186, v186, v192
	v_sub_f32_e32 v187, v187, v192
	v_sub_f32_e32 v188, v188, v192
	v_sub_f32_e32 v189, v189, v192
	v_sub_f32_e32 v190, v190, v192
	v_sub_f32_e32 v191, v191, v192
	v_pk_mul_f32 v[184:185], v[192:193], v[184:185] op_sel:[1,0]
	v_pk_mul_f32 v[186:187], v[192:193], v[186:187] op_sel:[1,0]
	v_pk_mul_f32 v[188:189], v[192:193], v[188:189] op_sel:[1,0]
	v_pk_mul_f32 v[190:191], v[192:193], v[190:191] op_sel:[1,0]
	v_pk_fma_f32 v[184:185], v[136:137], v[184:185], v[132:133]
	v_pk_fma_f32 v[186:187], v[138:139], v[186:187], v[134:135]
	v_pk_fma_f32 v[188:189], v[128:129], v[188:189], v[140:141]
	v_pk_fma_f32 v[190:191], v[130:131], v[190:191], v[142:143]
	v_pk_fma_f32 v[64:65], v[184:185], s[14:15], v[64:65] op_sel_hi:[1,0,1]
	v_pk_fma_f32 v[66:67], v[186:187], s[14:15], v[66:67] op_sel_hi:[1,0,1]
	v_pk_fma_f32 v[56:57], v[188:189], s[14:15], v[56:57] op_sel_hi:[1,0,1]
	v_pk_fma_f32 v[58:59], v[190:191], s[14:15], v[58:59] op_sel_hi:[1,0,1]
	global_store_dwordx4 v[218:219], v[64:67], off
	global_store_dwordx4 v[218:219], v[56:59], off offset:16
	v_lshl_add_u64 v[218:219], v[218:219], 0, s[98:99]
	global_load_dwordx2 v[192:193], v[168:169], off offset:384
	global_load_dwordx4 v[184:187], v[216:217], off
	global_load_dwordx4 v[188:191], v[216:217], off offset:16
	v_lshl_add_u64 v[216:217], v[216:217], 0, s[100:101]
	s_waitcnt vmcnt(5)
	v_sub_f32_e32 v232, v232, v240
	v_sub_f32_e32 v233, v233, v240
	v_sub_f32_e32 v234, v234, v240
	v_sub_f32_e32 v235, v235, v240
	v_sub_f32_e32 v236, v236, v240
	v_sub_f32_e32 v237, v237, v240
	v_sub_f32_e32 v238, v238, v240
	v_sub_f32_e32 v239, v239, v240
	v_pk_mul_f32 v[232:233], v[240:241], v[232:233] op_sel:[1,0]
	v_pk_mul_f32 v[234:235], v[240:241], v[234:235] op_sel:[1,0]
	v_pk_mul_f32 v[236:237], v[240:241], v[236:237] op_sel:[1,0]
	v_pk_mul_f32 v[238:239], v[240:241], v[238:239] op_sel:[1,0]
	v_pk_fma_f32 v[232:233], v[136:137], v[232:233], v[132:133]
	v_pk_fma_f32 v[234:235], v[138:139], v[234:235], v[134:135]
	v_pk_fma_f32 v[236:237], v[128:129], v[236:237], v[140:141]
	v_pk_fma_f32 v[238:239], v[130:131], v[238:239], v[142:143]
	v_pk_fma_f32 v[52:53], v[232:233], s[14:15], v[52:53] op_sel_hi:[1,0,1]
	v_pk_fma_f32 v[54:55], v[234:235], s[14:15], v[54:55] op_sel_hi:[1,0,1]
	v_pk_fma_f32 v[48:49], v[236:237], s[14:15], v[48:49] op_sel_hi:[1,0,1]
	v_pk_fma_f32 v[50:51], v[238:239], s[14:15], v[50:51] op_sel_hi:[1,0,1]
	global_store_dwordx4 v[218:219], v[52:55], off
	global_store_dwordx4 v[218:219], v[48:51], off offset:16
	v_lshl_add_u64 v[218:219], v[218:219], 0, s[98:99]
	global_load_dwordx2 v[240:241], v[168:169], off offset:1024
	global_load_dwordx4 v[232:235], v[216:217], off
	global_load_dwordx4 v[236:239], v[216:217], off offset:16
	v_lshl_add_u64 v[216:217], v[216:217], 0, s[98:99]
	s_waitcnt vmcnt(10)
;     __device__ __forceinline__ void operator()(const f32x4 (&acc)[2][2][4][2], const Unit& u, int wr, int wc, int fr, int fq) const {
;     ...
;                 for (int m = 0; m < 4; ++m) { const int row = row0 + ai * HALF + m * 16; const size_t p = (size_t)row * ldc + col0 + bj * HALF;
;                     const float mean = stats[2 * row], rstd = stats[2 * row + 1];
;                     const f32x4 r0 = *(const f32x4*)(res + p), r1 = *(const f32x4*)(res + p + 4);
;                     const f32x4 n0 = (r0 - mean) * rstd * g0 + b0, n1 = (r1 - mean) * rstd * g1 + b1;
;                     *(f32x4*)(out + p) = n0 * alpha + acc[ai][bj][m][0]; *(f32x4*)(out + p + 4) = n1 * alpha + acc[ai][bj][m][1]; }
	v_sub_f32_e32 v244, v244, v242
	v_sub_f32_e32 v245, v245, v242
	v_sub_f32_e32 v246, v246, v242
	v_sub_f32_e32 v247, v247, v242
	v_sub_f32_e32 v248, v248, v242
	v_sub_f32_e32 v249, v249, v242
	v_sub_f32_e32 v250, v250, v242
	v_sub_f32_e32 v251, v251, v242
	v_pk_mul_f32 v[244:245], v[242:243], v[244:245] op_sel:[1,0]
	v_pk_mul_f32 v[246:247], v[242:243], v[246:247] op_sel:[1,0]
	v_pk_mul_f32 v[248:249], v[242:243], v[248:249] op_sel:[1,0]
	v_pk_mul_f32 v[250:251], v[242:243], v[250:251] op_sel:[1,0]
	v_pk_fma_f32 v[244:245], v[136:137], v[244:245], v[132:133]
	v_pk_fma_f32 v[246:247], v[138:139], v[246:247], v[134:135]
	v_pk_fma_f32 v[248:249], v[128:129], v[248:249], v[140:141]
	v_pk_fma_f32 v[250:251], v[130:131], v[250:251], v[142:143]
	v_pk_fma_f32 v[44:45], v[244:245], s[14:15], v[44:45] op_sel_hi:[1,0,1]
	v_pk_fma_f32 v[46:47], v[246:247], s[14:15], v[46:47] op_sel_hi:[1,0,1]
	v_pk_fma_f32 v[40:41], v[248:249], s[14:15], v[40:41] op_sel_hi:[1,0,1]
	v_pk_fma_f32 v[42:43], v[250:251], s[14:15], v[42:43] op_sel_hi:[1,0,1]
	global_store_dwordx4 v[218:219], v[44:47], off
	global_store_dwordx4 v[218:219], v[40:43], off offset:16
	v_lshl_add_u64 v[218:219], v[218:219], 0, s[98:99]
	global_load_dwordx2 v[242:243], v[168:169], off offset:1152
	global_load_dwordx4 v[244:247], v[216:217], off
	global_load_dwordx4 v[248:251], v[216:217], off offset:16
	v_lshl_add_u64 v[216:217], v[216:217], 0, s[98:99]
	s_waitcnt vmcnt(10)
	v_sub_f32_e32 v184, v184, v192
	v_sub_f32_e32 v185, v185, v192
	v_sub_f32_e32 v186, v186, v192
	v_sub_f32_e32 v187, v187, v192
	v_sub_f32_e32 v188, v188, v192
	v_sub_f32_e32 v189, v189, v192
	v_sub_f32_e32 v190, v190, v192
	v_sub_f32_e32 v191, v191, v192
	v_pk_mul_f32 v[184:185], v[192:193], v[184:185] op_sel:[1,0]
	v_pk_mul_f32 v[186:187], v[192:193], v[186:187] op_sel:[1,0]
	v_pk_mul_f32 v[188:189], v[192:193], v[188:189] op_sel:[1,0]
	v_pk_mul_f32 v[190:191], v[192:193], v[190:191] op_sel:[1,0]
	v_pk_fma_f32 v[184:185], v[136:137], v[184:185], v[132:133]
	v_pk_fma_f32 v[186:187], v[138:139], v[186:187], v[134:135]
	v_pk_fma_f32 v[188:189], v[128:129], v[188:189], v[140:141]
	v_pk_fma_f32 v[190:191], v[130:131], v[190:191], v[142:143]
	v_pk_fma_f32 v[36:37], v[184:185], s[14:15], v[36:37] op_sel_hi:[1,0,1]
	v_pk_fma_f32 v[38:39], v[186:187], s[14:15], v[38:39] op_sel_hi:[1,0,1]
	v_pk_fma_f32 v[32:33], v[188:189], s[14:15], v[32:33] op_sel_hi:[1,0,1]
	v_pk_fma_f32 v[34:35], v[190:191], s[14:15], v[34:35] op_sel_hi:[1,0,1]
	global_store_dwordx4 v[218:219], v[36:39], off
	global_store_dwordx4 v[218:219], v[32:35], off offset:16
	v_lshl_add_u64 v[218:219], v[218:219], 0, s[100:101]
	global_load_dwordx2 v[192:193], v[168:169], off offset:1280
	global_load_dwordx4 v[184:187], v[216:217], off
	global_load_dwordx4 v[188:191], v[216:217], off offset:16
	v_lshl_add_u64 v[216:217], v[216:217], 0, s[98:99]
	s_waitcnt vmcnt(10)
	v_sub_f32_e32 v232, v232, v240
	v_sub_f32_e32 v233, v233, v240
	v_sub_f32_e32 v234, v234, v240
	v_sub_f32_e32 v235, v235, v240
	v_sub_f32_e32 v236, v236, v240
	v_sub_f32_e32 v237, v237, v240
	v_sub_f32_e32 v238, v238, v240
	v_sub_f32_e32 v239, v239, v240
	v_pk_mul_f32 v[232:233], v[240:241], v[232:233] op_sel:[1,0]
	v_pk_mul_f32 v[234:235], v[240:241], v[234:235] op_sel:[1,0]
	v_pk_mul_f32 v[236:237], v[240:241], v[236:237] op_sel:[1,0]
	v_pk_mul_f32 v[238:239], v[240:241], v[238:239] op_sel:[1,0]
	v_pk_fma_f32 v[232:233], v[136:137], v[232:233], v[132:133]
	v_pk_fma_f32 v[234:235], v[138:139], v[234:235], v[134:135]
	v_pk_fma_f32 v[236:237], v[128:129], v[236:237], v[140:141]
	v_pk_fma_f32 v[238:239], v[130:131], v[238:239], v[142:143]
	v_pk_fma_f32 v[28:29], v[232:233], s[14:15], v[28:29] op_sel_hi:[1,0,1]
	v_pk_fma_f32 v[30:31], v[234:235], s[14:15], v[30:31] op_sel_hi:[1,0,1]
	v_pk_fma_f32 v[24:25], v[236:237], s[14:15], v[24:25] op_sel_hi:[1,0,1]
	v_pk_fma_f32 v[26:27], v[238:239], s[14:15], v[26:27] op_sel_hi:[1,0,1]
	global_store_dwordx4 v[218:219], v[28:31], off
	global_store_dwordx4 v[218:219], v[24:27], off offset:16
	v_lshl_add_u64 v[218:219], v[218:219], 0, s[98:99]
	global_load_dwordx2 v[240:241], v[168:169], off offset:1408
	global_load_dwordx4 v[232:235], v[216:217], off
	global_load_dwordx4 v[236:239], v[216:217], off offset:16
	s_waitcnt vmcnt(10)
;     __device__ __forceinline__ void operator()(const f32x4 (&acc)[2][2][4][2], const Unit& u, int wr, int wc, int fr, int fq) const {
;     ...
;                 for (int m = 0; m < 4; ++m) { const int row = row0 + ai * HALF + m * 16; const size_t p = (size_t)row * ldc + col0 + bj * HALF;
;                     const float mean = stats[2 * row], rstd = stats[2 * row + 1];
;                     const f32x4 r0 = *(const f32x4*)(res + p), r1 = *(const f32x4*)(res + p + 4);
;                     const f32x4 n0 = (r0 - mean) * rstd * g0 + b0, n1 = (r1 - mean) * rstd * g1 + b1;
;                     *(f32x4*)(out + p) = n0 * alpha + acc[ai][bj][m][0]; *(f32x4*)(out + p + 4) = n1 * alpha + acc[ai][bj][m][1]; }
	v_sub_f32_e32 v244, v244, v242
	v_sub_f32_e32 v245, v245, v242
	v_sub_f32_e32 v246, v246, v242
	v_sub_f32_e32 v247, v247, v242
	v_sub_f32_e32 v248, v248, v242
	v_sub_f32_e32 v249, v249, v242
	v_sub_f32_e32 v250, v250, v242
	v_sub_f32_e32 v251, v251, v242
	v_pk_mul_f32 v[244:245], v[242:243], v[244:245] op_sel:[1,0]
	v_pk_mul_f32 v[246:247], v[242:243], v[246:247] op_sel:[1,0]
	v_pk_mul_f32 v[248:249], v[242:243], v[248:249] op_sel:[1,0]
	v_pk_mul_f32 v[250:251], v[242:243], v[250:251] op_sel:[1,0]
	v_pk_fma_f32 v[244:245], v[136:137], v[244:245], v[132:133]
	v_pk_fma_f32 v[246:247], v[138:139], v[246:247], v[134:135]
	v_pk_fma_f32 v[248:249], v[128:129], v[248:249], v[140:141]
	v_pk_fma_f32 v[250:251], v[130:131], v[250:251], v[142:143]
	v_pk_fma_f32 v[20:21], v[244:245], s[14:15], v[20:21] op_sel_hi:[1,0,1]
	v_pk_fma_f32 v[22:23], v[246:247], s[14:15], v[22:23] op_sel_hi:[1,0,1]
	v_pk_fma_f32 v[16:17], v[248:249], s[14:15], v[16:17] op_sel_hi:[1,0,1]
	v_pk_fma_f32 v[18:19], v[250:251], s[14:15], v[18:19] op_sel_hi:[1,0,1]
	global_store_dwordx4 v[218:219], v[20:23], off
	global_store_dwordx4 v[218:219], v[16:19], off offset:16
	v_lshl_add_u64 v[218:219], v[218:219], 0, s[98:99]
	s_waitcnt vmcnt(7)
	v_sub_f32_e32 v184, v184, v192
	v_sub_f32_e32 v185, v185, v192
	v_sub_f32_e32 v186, v186, v192
	v_sub_f32_e32 v187, v187, v192
	v_sub_f32_e32 v188, v188, v192
	v_sub_f32_e32 v189, v189, v192
	v_sub_f32_e32 v190, v190, v192
	v_sub_f32_e32 v191, v191, v192
	v_pk_mul_f32 v[184:185], v[192:193], v[184:185] op_sel:[1,0]
	v_pk_mul_f32 v[186:187], v[192:193], v[186:187] op_sel:[1,0]
	v_pk_mul_f32 v[188:189], v[192:193], v[188:189] op_sel:[1,0]
	v_pk_mul_f32 v[190:191], v[192:193], v[190:191] op_sel:[1,0]
	v_pk_fma_f32 v[184:185], v[136:137], v[184:185], v[132:133]
	v_pk_fma_f32 v[186:187], v[138:139], v[186:187], v[134:135]
	v_pk_fma_f32 v[188:189], v[128:129], v[188:189], v[140:141]
	v_pk_fma_f32 v[190:191], v[130:131], v[190:191], v[142:143]
	v_pk_fma_f32 v[12:13], v[184:185], s[14:15], v[12:13] op_sel_hi:[1,0,1]
	v_pk_fma_f32 v[14:15], v[186:187], s[14:15], v[14:15] op_sel_hi:[1,0,1]
	v_pk_fma_f32 v[8:9], v[188:189], s[14:15], v[8:9] op_sel_hi:[1,0,1]
	v_pk_fma_f32 v[10:11], v[190:191], s[14:15], v[10:11] op_sel_hi:[1,0,1]
	global_store_dwordx4 v[218:219], v[12:15], off
	global_store_dwordx4 v[218:219], v[8:11], off offset:16
	v_lshl_add_u64 v[218:219], v[218:219], 0, s[98:99]
	s_waitcnt vmcnt(4)
	v_sub_f32_e32 v232, v232, v240
	v_sub_f32_e32 v233, v233, v240
	v_sub_f32_e32 v234, v234, v240
	v_sub_f32_e32 v235, v235, v240
	v_sub_f32_e32 v236, v236, v240
	v_sub_f32_e32 v237, v237, v240
	v_sub_f32_e32 v238, v238, v240
	v_sub_f32_e32 v239, v239, v240
	v_pk_mul_f32 v[232:233], v[240:241], v[232:233] op_sel:[1,0]
	v_pk_mul_f32 v[234:235], v[240:241], v[234:235] op_sel:[1,0]
	v_pk_mul_f32 v[236:237], v[240:241], v[236:237] op_sel:[1,0]
	v_pk_mul_f32 v[238:239], v[240:241], v[238:239] op_sel:[1,0]
	v_pk_fma_f32 v[232:233], v[136:137], v[232:233], v[132:133]
	v_pk_fma_f32 v[234:235], v[138:139], v[234:235], v[134:135]
	v_pk_fma_f32 v[236:237], v[128:129], v[236:237], v[140:141]
	v_pk_fma_f32 v[238:239], v[130:131], v[238:239], v[142:143]
	v_pk_fma_f32 v[4:5], v[232:233], s[14:15], v[4:5] op_sel_hi:[1,0,1]
	v_pk_fma_f32 v[6:7], v[234:235], s[14:15], v[6:7] op_sel_hi:[1,0,1]
	v_pk_fma_f32 v[0:1], v[236:237], s[14:15], v[0:1] op_sel_hi:[1,0,1]
	v_pk_fma_f32 v[2:3], v[238:239], s[14:15], v[2:3] op_sel_hi:[1,0,1]
	global_store_dwordx4 v[218:219], v[4:7], off
	global_store_dwordx4 v[218:219], v[0:3], off offset:16
	s_cbranch_vccnz .LBB0_800
	s_andn2_b64 vcc, exec, s[6:7]
	s_cbranch_vccnz .LBB0_799
	s_barrier
	s_branch .LBB0_799

;     __device__ __forceinline__ void operator()(const f32x4 (&acc)[2][2][4][2], const Unit& u, int wr, int wc, int fr, int fq) const {
;         const int row0 = u.pm * BM + wr * 64 + fr; const int col0 = u.pn * BM + wc * 32 + 8 * fq;
; #pragma unroll
;         for (int bj = 0; bj < 2; ++bj) {
;             const f32x4 g0 = *(const f32x4*)(g + col0 + bj * HALF), g1 = *(const f32x4*)(g + col0 + bj * HALF + 4);
;             const f32x4 b0 = *(const f32x4*)(b + col0 + bj * HALF), b1 = *(const f32x4*)(b + col0 + bj * HALF + 4);
; #pragma unroll
;             for (int ai = 0; ai < 2; ++ai)
; #pragma unroll
;                 for (int m = 0; m < 4; ++m) { const int row = row0 + ai * HALF + m * 16; const size_t p = (size_t)row * ldc + col0 + bj * HALF;
;                     const float mean = stats[2 * row], rstd = stats[2 * row + 1];
;                     const f32x4 r0 = *(const f32x4*)(res + p), r1 = *(const f32x4*)(res + p + 4);
;                     const f32x4 n0 = (r0 - mean) * rstd * g0 + b0, n1 = (r1 - mean) * rstd * g1 + b1;
;                     *(f32x4*)(out + p) = n0 * alpha + acc[ai][bj][m][0]; *(f32x4*)(out + p + 4) = n1 * alpha + acc[ai][bj][m][1]; }
.LBB0_1272:
	v_lshl_or_b32 v128, s51, 8, v180
	v_lshl_add_u32 v178, s36, 8, v145
	v_ashrrev_i32_e32 v129, 31, v128
	v_lshlrev_b64 v[176:177], 2, v[128:129]
	v_lshlrev_b32_e32 v128, 1, v178
	v_ashrrev_i32_e32 v179, 31, v178
	v_ashrrev_i32_e32 v129, 31, v128
	v_lshl_add_u64 v[168:169], v[128:129], 2, s[8:9]
	v_lshlrev_b64 v[128:129], 13, v[178:179]
	v_lshl_add_u64 v[128:129], s[20:21], 0, v[128:129]
	v_lshl_add_u64 v[164:165], v[128:129], 0, v[176:177]
	v_lshl_add_u64 v[172:173], s[94:95], 0, v[176:177]
	v_lshl_add_u64 v[170:171], s[92:93], 0, v[176:177]
	v_or_b32_e32 v166, 16, v178
	v_ashrrev_i32_e32 v167, 31, v166
	v_lshlrev_b32_e32 v174, 1, v166
	v_ashrrev_i32_e32 v175, 31, v174
	v_lshlrev_b64 v[166:167], 13, v[166:167]
	v_lshl_add_u64 v[174:175], v[174:175], 2, s[8:9]
	v_lshl_add_u64 v[166:167], s[20:21], 0, v[166:167]
	v_lshl_add_u64 v[166:167], v[166:167], 0, v[176:177]
	s_andn2_b64 vcc, exec, s[0:1]
	s_mov_b64 s[0:1], -1
	v_mov_b64_e32 v[216:217], v[164:165]
	v_mov_b64_e32 v[218:219], v[164:165]
	s_mov_b64 s[98:99], 0x20000
	s_mov_b64 s[100:101], 0xa0000
	v_mov_b32_e32 v220, 0x200
	v_mov_b32_e32 v221, 0
	global_load_dwordx4 v[128:131], v[170:171], off offset:16
	global_load_dwordx4 v[132:135], v[172:173], off
	global_load_dwordx4 v[136:139], v[170:171], off
	global_load_dwordx4 v[140:143], v[172:173], off offset:16
	global_load_dwordx2 v[240:241], v[168:169], off
	global_load_dwordx4 v[232:235], v[216:217], off
	global_load_dwordx4 v[236:239], v[216:217], off offset:16
	v_lshl_add_u64 v[216:217], v[216:217], 0, s[98:99]
	global_load_dwordx2 v[242:243], v[168:169], off offset:128
	global_load_dwordx4 v[244:247], v[216:217], off
	global_load_dwordx4 v[248:251], v[216:217], off offset:16
	v_lshl_add_u64 v[216:217], v[216:217], 0, s[98:99]
	global_load_dwordx2 v[192:193], v[168:169], off offset:256
	global_load_dwordx4 v[184:187], v[216:217], off
	global_load_dwordx4 v[188:191], v[216:217], off offset:16
	v_lshl_add_u64 v[216:217], v[216:217], 0, s[98:99]
	s_waitcnt vmcnt(6)
	v_sub_f32_e32 v232, v232, v240
	v_sub_f32_e32 v233, v233, v240
	v_sub_f32_e32 v234, v234, v240
	v_sub_f32_e32 v235, v235, v240
	v_sub_f32_e32 v236, v236, v240
	v_sub_f32_e32 v237, v237, v240
	v_sub_f32_e32 v238, v238, v240
	v_sub_f32_e32 v239, v239, v240
	v_pk_mul_f32 v[232:233], v[240:241], v[232:233] op_sel:[1,0]
	v_pk_mul_f32 v[234:235], v[240:241], v[234:235] op_sel:[1,0]
	v_pk_mul_f32 v[236:237], v[240:241], v[236:237] op_sel:[1,0]
	v_pk_mul_f32 v[238:239], v[240:241], v[238:239] op_sel:[1,0]
	v_pk_fma_f32 v[232:233], v[136:137], v[232:233], v[132:133]
	v_pk_fma_f32 v[234:235], v[138:139], v[234:235], v[134:135]
	v_pk_fma_f32 v[236:237], v[128:129], v[236:237], v[140:141]
	v_pk_fma_f32 v[238:239], v[130:131], v[238:239], v[142:143]
	v_pk_fma_f32 v[124:125], v[232:233], s[14:15], v[124:125] op_sel_hi:[1,0,1]
	v_pk_fma_f32 v[126:127], v[234:235], s[14:15], v[126:127] op_sel_hi:[1,0,1]
	v_pk_fma_f32 v[120:121], v[236:237], s[14:15], v[120:121] op_sel_hi:[1,0,1]
	v_pk_fma_f32 v[122:123], v[238:239], s[14:15], v[122:123] op_sel_hi:[1,0,1]
	global_store_dwordx4 v[218:219], v[124:127], off
	global_store_dwordx4 v[218:219], v[120:123], off offset:16
	v_lshl_add_u64 v[218:219], v[218:219], 0, s[98:99]
	global_load_dwordx2 v[240:241], v[168:169], off offset:384
	global_load_dwordx4 v[232:235], v[216:217], off
	global_load_dwordx4 v[236:239], v[216:217], off offset:16
	v_lshl_add_u64 v[216:217], v[216:217], 0, s[100:101]
	s_waitcnt vmcnt(8)
	v_sub_f32_e32 v244, v244, v242
	v_sub_f32_e32 v245, v245, v242
	v_sub_f32_e32 v246, v246, v242
	v_sub_f32_e32 v247, v247, v242
	v_sub_f32_e32 v248, v248, v242
	v_sub_f32_e32 v249, v249, v242
	v_sub_f32_e32 v250, v250, v242
	v_sub_f32_e32 v251, v251, v242
	v_pk_mul_f32 v[244:245], v[242:243], v[244:245] op_sel:[1,0]
	v_pk_mul_f32 v[246:247], v[242:243], v[246:247] op_sel:[1,0]
	v_pk_mul_f32 v[248:249], v[242:243], v[248:249] op_sel:[1,0]
	v_pk_mul_f32 v[250:251], v[242:243], v[250:251] op_sel:[1,0]
	v_pk_fma_f32 v[244:245], v[136:137], v[244:245], v[132:133]
	v_pk_fma_f32 v[246:247], v[138:139], v[246:247], v[134:135]
	v_pk_fma_f32 v[248:249], v[128:129], v[248:249], v[140:141]
	v_pk_fma_f32 v[250:251], v[130:131], v[250:251], v[142:143]
	v_pk_fma_f32 v[116:117], v[244:245], s[14:15], v[116:117] op_sel_hi:[1,0,1]
	v_pk_fma_f32 v[118:119], v[246:247], s[14:15], v[118:119] op_sel_hi:[1,0,1]
	v_pk_fma_f32 v[112:113], v[248:249], s[14:15], v[112:113] op_sel_hi:[1,0,1]
	v_pk_fma_f32 v[114:115], v[250:251], s[14:15], v[114:115] op_sel_hi:[1,0,1]
	global_store_dwordx4 v[218:219], v[116:119], off
	global_store_dwordx4 v[218:219], v[112:115], off offset:16
	v_lshl_add_u64 v[218:219], v[218:219], 0, s[98:99]
	global_load_dwordx2 v[242:243], v[168:169], off offset:1024
	global_load_dwordx4 v[244:247], v[216:217], off
	global_load_dwordx4 v[248:251], v[216:217], off offset:16
	v_lshl_add_u64 v[216:217], v[216:217], 0, s[98:99]
	s_waitcnt vmcnt(10)
;     __device__ __forceinline__ void operator()(const f32x4 (&acc)[2][2][4][2], const Unit& u, int wr, int wc, int fr, int fq) const {
;     ...
;                 for (int m = 0; m < 4; ++m) { const int row = row0 + ai * HALF + m * 16; const size_t p = (size_t)row * ldc + col0 + bj * HALF;
;                     const float mean = stats[2 * row], rstd = stats[2 * row + 1];
;                     const f32x4 r0 = *(const f32x4*)(res + p), r1 = *(const f32x4*)(res + p + 4);
;                     const f32x4 n0 = (r0 - mean) * rstd * g0 + b0, n1 = (r1 - mean) * rstd * g1 + b1;
;                     *(f32x4*)(out + p) = n0 * alpha + acc[ai][bj][m][0]; *(f32x4*)(out + p + 4) = n1 * alpha + acc[ai][bj][m][1]; }
	v_sub_f32_e32 v184, v184, v192
	v_sub_f32_e32 v185, v185, v192
	v_sub_f32_e32 v186, v186, v192
	v_sub_f32_e32 v187, v187, v192
	v_sub_f32_e32 v188, v188, v192
	v_sub_f32_e32 v189, v189, v192
	v_sub_f32_e32 v190, v190, v192
	v_sub_f32_e32 v191, v191, v192
	v_pk_mul_f32 v[184:185], v[192:193], v[184:185] op_sel:[1,0]
	v_pk_mul_f32 v[186:187], v[192:193], v[186:187] op_sel:[1,0]
	v_pk_mul_f32 v[188:189], v[192:193], v[188:189] op_sel:[1,0]
	v_pk_mul_f32 v[190:191], v[192:193], v[190:191] op_sel:[1,0]
	v_pk_fma_f32 v[184:185], v[136:137], v[184:185], v[132:133]
	v_pk_fma_f32 v[186:187], v[138:139], v[186:187], v[134:135]
	v_pk_fma_f32 v[188:189], v[128:129], v[188:189], v[140:141]
	v_pk_fma_f32 v[190:191], v[130:131], v[190:191], v[142:143]
	v_pk_fma_f32 v[108:109], v[184:185], s[14:15], v[108:109] op_sel_hi:[1,0,1]
	v_pk_fma_f32 v[110:111], v[186:187], s[14:15], v[110:111] op_sel_hi:[1,0,1]
	v_pk_fma_f32 v[104:105], v[188:189], s[14:15], v[104:105] op_sel_hi:[1,0,1]
	v_pk_fma_f32 v[106:107], v[190:191], s[14:15], v[106:107] op_sel_hi:[1,0,1]
	global_store_dwordx4 v[218:219], v[108:111], off
	global_store_dwordx4 v[218:219], v[104:107], off offset:16
	v_lshl_add_u64 v[218:219], v[218:219], 0, s[98:99]
	global_load_dwordx2 v[192:193], v[168:169], off offset:1152
	global_load_dwordx4 v[184:187], v[216:217], off
	global_load_dwordx4 v[188:191], v[216:217], off offset:16
	v_lshl_add_u64 v[216:217], v[216:217], 0, s[98:99]
	s_waitcnt vmcnt(10)
	v_sub_f32_e32 v232, v232, v240
	v_sub_f32_e32 v233, v233, v240
	v_sub_f32_e32 v234, v234, v240
	v_sub_f32_e32 v235, v235, v240
	v_sub_f32_e32 v236, v236, v240
	v_sub_f32_e32 v237, v237, v240
	v_sub_f32_e32 v238, v238, v240
	v_sub_f32_e32 v239, v239, v240
	v_pk_mul_f32 v[232:233], v[240:241], v[232:233] op_sel:[1,0]
	v_pk_mul_f32 v[234:235], v[240:241], v[234:235] op_sel:[1,0]
	v_pk_mul_f32 v[236:237], v[240:241], v[236:237] op_sel:[1,0]
	v_pk_mul_f32 v[238:239], v[240:241], v[238:239] op_sel:[1,0]
	v_pk_fma_f32 v[232:233], v[136:137], v[232:233], v[132:133]
	v_pk_fma_f32 v[234:235], v[138:139], v[234:235], v[134:135]
	v_pk_fma_f32 v[236:237], v[128:129], v[236:237], v[140:141]
	v_pk_fma_f32 v[238:239], v[130:131], v[238:239], v[142:143]
	v_pk_fma_f32 v[100:101], v[232:233], s[14:15], v[100:101] op_sel_hi:[1,0,1]
	v_pk_fma_f32 v[102:103], v[234:235], s[14:15], v[102:103] op_sel_hi:[1,0,1]
	v_pk_fma_f32 v[96:97], v[236:237], s[14:15], v[96:97] op_sel_hi:[1,0,1]
	v_pk_fma_f32 v[98:99], v[238:239], s[14:15], v[98:99] op_sel_hi:[1,0,1]
	global_store_dwordx4 v[218:219], v[100:103], off
	global_store_dwordx4 v[218:219], v[96:99], off offset:16
	v_lshl_add_u64 v[218:219], v[218:219], 0, s[100:101]
	global_load_dwordx2 v[240:241], v[168:169], off offset:1280
	global_load_dwordx4 v[232:235], v[216:217], off
	global_load_dwordx4 v[236:239], v[216:217], off offset:16
	v_lshl_add_u64 v[216:217], v[216:217], 0, s[98:99]
	s_waitcnt vmcnt(10)
	v_sub_f32_e32 v244, v244, v242
	v_sub_f32_e32 v245, v245, v242
	v_sub_f32_e32 v246, v246, v242
	v_sub_f32_e32 v247, v247, v242
	v_sub_f32_e32 v248, v248, v242
	v_sub_f32_e32 v249, v249, v242
	v_sub_f32_e32 v250, v250, v242
	v_sub_f32_e32 v251, v251, v242
	v_pk_mul_f32 v[244:245], v[242:243], v[244:245] op_sel:[1,0]
	v_pk_mul_f32 v[246:247], v[242:243], v[246:247] op_sel:[1,0]
	v_pk_mul_f32 v[248:249], v[242:243], v[248:249] op_sel:[1,0]
	v_pk_mul_f32 v[250:251], v[242:243], v[250:251] op_sel:[1,0]
	v_pk_fma_f32 v[244:245], v[136:137], v[244:245], v[132:133]
	v_pk_fma_f32 v[246:247], v[138:139], v[246:247], v[134:135]
	v_pk_fma_f32 v[248:249], v[128:129], v[248:249], v[140:141]
	v_pk_fma_f32 v[250:251], v[130:131], v[250:251], v[142:143]
	v_pk_fma_f32 v[92:93], v[244:245], s[14:15], v[92:93] op_sel_hi:[1,0,1]
	v_pk_fma_f32 v[94:95], v[246:247], s[14:15], v[94:95] op_sel_hi:[1,0,1]
	v_pk_fma_f32 v[88:89], v[248:249], s[14:15], v[88:89] op_sel_hi:[1,0,1]
	v_pk_fma_f32 v[90:91], v[250:251], s[14:15], v[90:91] op_sel_hi:[1,0,1]
	global_store_dwordx4 v[218:219], v[92:95], off
	global_store_dwordx4 v[218:219], v[88:91], off offset:16
	v_lshl_add_u64 v[218:219], v[218:219], 0, s[98:99]
	global_load_dwordx2 v[242:243], v[168:169], off offset:1408
	global_load_dwordx4 v[244:247], v[216:217], off
	global_load_dwordx4 v[248:251], v[216:217], off offset:16
	v_lshl_add_u64 v[216:217], v[220:221], 0, v[164:165]
	s_waitcnt vmcnt(10)
	v_sub_f32_e32 v184, v184, v192
	v_sub_f32_e32 v185, v185, v192
	v_sub_f32_e32 v186, v186, v192
	v_sub_f32_e32 v187, v187, v192
	v_sub_f32_e32 v188, v188, v192
	v_sub_f32_e32 v189, v189, v192
	v_sub_f32_e32 v190, v190, v192
	v_sub_f32_e32 v191, v191, v192
	v_pk_mul_f32 v[184:185], v[192:193], v[184:185] op_sel:[1,0]
	v_pk_mul_f32 v[186:187], v[192:193], v[186:187] op_sel:[1,0]
	v_pk_mul_f32 v[188:189], v[192:193], v[188:189] op_sel:[1,0]
	v_pk_mul_f32 v[190:191], v[192:193], v[190:191] op_sel:[1,0]
	v_pk_fma_f32 v[184:185], v[136:137], v[184:185], v[132:133]
	v_pk_fma_f32 v[186:187], v[138:139], v[186:187], v[134:135]
	v_pk_fma_f32 v[188:189], v[128:129], v[188:189], v[140:141]
	v_pk_fma_f32 v[190:191], v[130:131], v[190:191], v[142:143]
	v_pk_fma_f32 v[84:85], v[184:185], s[14:15], v[84:85] op_sel_hi:[1,0,1]
	v_pk_fma_f32 v[86:87], v[186:187], s[14:15], v[86:87] op_sel_hi:[1,0,1]
	v_pk_fma_f32 v[80:81], v[188:189], s[14:15], v[80:81] op_sel_hi:[1,0,1]
	v_pk_fma_f32 v[82:83], v[190:191], s[14:15], v[82:83] op_sel_hi:[1,0,1]
	global_store_dwordx4 v[218:219], v[84:87], off
	global_store_dwordx4 v[218:219], v[80:83], off offset:16
	v_lshl_add_u64 v[218:219], v[218:219], 0, s[98:99]
	global_load_dwordx2 v[192:193], v[168:169], off
	global_load_dwordx4 v[184:187], v[216:217], off
	global_load_dwordx4 v[188:191], v[216:217], off offset:16
	v_lshl_add_u64 v[216:217], v[216:217], 0, s[98:99]
	s_waitcnt vmcnt(10)
;     __device__ __forceinline__ void operator()(const f32x4 (&acc)[2][2][4][2], const Unit& u, int wr, int wc, int fr, int fq) const {
;     ...
;         for (int bj = 0; bj < 2; ++bj) {
;             const f32x4 g0 = *(const f32x4*)(g + col0 + bj * HALF), g1 = *(const f32x4*)(g + col0 + bj * HALF + 4);
;             const f32x4 b0 = *(const f32x4*)(b + col0 + bj * HALF), b1 = *(const f32x4*)(b + col0 + bj * HALF + 4);
; #pragma unroll
;             for (int ai = 0; ai < 2; ++ai)
; #pragma unroll
;                 for (int m = 0; m < 4; ++m) { const int row = row0 + ai * HALF + m * 16; const size_t p = (size_t)row * ldc + col0 + bj * HALF;
;                     const float mean = stats[2 * row], rstd = stats[2 * row + 1];
;                     const f32x4 r0 = *(const f32x4*)(res + p), r1 = *(const f32x4*)(res + p + 4);
;                     const f32x4 n0 = (r0 - mean) * rstd * g0 + b0, n1 = (r1 - mean) * rstd * g1 + b1;
;                     *(f32x4*)(out + p) = n0 * alpha + acc[ai][bj][m][0]; *(f32x4*)(out + p + 4) = n1 * alpha + acc[ai][bj][m][1]; }
	v_sub_f32_e32 v232, v232, v240
	v_sub_f32_e32 v233, v233, v240
	v_sub_f32_e32 v234, v234, v240
	v_sub_f32_e32 v235, v235, v240
	v_sub_f32_e32 v236, v236, v240
	v_sub_f32_e32 v237, v237, v240
	v_sub_f32_e32 v238, v238, v240
	v_sub_f32_e32 v239, v239, v240
	v_pk_mul_f32 v[232:233], v[240:241], v[232:233] op_sel:[1,0]
	v_pk_mul_f32 v[234:235], v[240:241], v[234:235] op_sel:[1,0]
	v_pk_mul_f32 v[236:237], v[240:241], v[236:237] op_sel:[1,0]
	v_pk_mul_f32 v[238:239], v[240:241], v[238:239] op_sel:[1,0]
	v_pk_fma_f32 v[232:233], v[136:137], v[232:233], v[132:133]
	v_pk_fma_f32 v[234:235], v[138:139], v[234:235], v[134:135]
	v_pk_fma_f32 v[236:237], v[128:129], v[236:237], v[140:141]
	v_pk_fma_f32 v[238:239], v[130:131], v[238:239], v[142:143]
	v_pk_fma_f32 v[76:77], v[232:233], s[14:15], v[76:77] op_sel_hi:[1,0,1]
	v_pk_fma_f32 v[78:79], v[234:235], s[14:15], v[78:79] op_sel_hi:[1,0,1]
	v_pk_fma_f32 v[72:73], v[236:237], s[14:15], v[72:73] op_sel_hi:[1,0,1]
	v_pk_fma_f32 v[74:75], v[238:239], s[14:15], v[74:75] op_sel_hi:[1,0,1]
	global_store_dwordx4 v[218:219], v[76:79], off
	global_store_dwordx4 v[218:219], v[72:75], off offset:16
	v_lshl_add_u64 v[218:219], v[218:219], 0, s[98:99]
	global_load_dwordx2 v[240:241], v[168:169], off offset:128
	global_load_dwordx4 v[232:235], v[216:217], off
	global_load_dwordx4 v[236:239], v[216:217], off offset:16
	v_lshl_add_u64 v[216:217], v[216:217], 0, s[98:99]
	s_waitcnt vmcnt(10)
	v_sub_f32_e32 v244, v244, v242
	v_sub_f32_e32 v245, v245, v242
	v_sub_f32_e32 v246, v246, v242
	v_sub_f32_e32 v247, v247, v242
	v_sub_f32_e32 v248, v248, v242
	v_sub_f32_e32 v249, v249, v242
	v_sub_f32_e32 v250, v250, v242
	v_sub_f32_e32 v251, v251, v242
	v_pk_mul_f32 v[244:245], v[242:243], v[244:245] op_sel:[1,0]
	v_pk_mul_f32 v[246:247], v[242:243], v[246:247] op_sel:[1,0]
	v_pk_mul_f32 v[248:249], v[242:243], v[248:249] op_sel:[1,0]
	v_pk_mul_f32 v[250:251], v[242:243], v[250:251] op_sel:[1,0]
	v_pk_fma_f32 v[244:245], v[136:137], v[244:245], v[132:133]
	v_pk_fma_f32 v[246:247], v[138:139], v[246:247], v[134:135]
	v_pk_fma_f32 v[248:249], v[128:129], v[248:249], v[140:141]
	v_pk_fma_f32 v[250:251], v[130:131], v[250:251], v[142:143]
	v_pk_fma_f32 v[68:69], v[244:245], s[14:15], v[68:69] op_sel_hi:[1,0,1]
	v_pk_fma_f32 v[70:71], v[246:247], s[14:15], v[70:71] op_sel_hi:[1,0,1]
	v_pk_fma_f32 v[60:61], v[248:249], s[14:15], v[60:61] op_sel_hi:[1,0,1]
	v_pk_fma_f32 v[62:63], v[250:251], s[14:15], v[62:63] op_sel_hi:[1,0,1]
	global_store_dwordx4 v[218:219], v[68:71], off
	global_store_dwordx4 v[218:219], v[60:63], off offset:16
	v_lshl_add_u64 v[218:219], v[220:221], 0, v[164:165]
	global_load_dwordx2 v[242:243], v[168:169], off offset:256
	global_load_dwordx4 v[244:247], v[216:217], off
	global_load_dwordx4 v[248:251], v[216:217], off offset:16
	v_lshl_add_u64 v[216:217], v[216:217], 0, s[98:99]
	global_load_dwordx4 v[128:131], v[170:171], off offset:528
	global_load_dwordx4 v[132:135], v[172:173], off offset:512
	global_load_dwordx4 v[136:139], v[170:171], off offset:512
	global_load_dwordx4 v[140:143], v[172:173], off offset:528
	s_waitcnt vmcnt(0)
	v_sub_f32_e32 v184, v184, v192
	v_sub_f32_e32 v185, v185, v192
	v_sub_f32_e32 v186, v186, v192
	v_sub_f32_e32 v187, v187, v192
	v_sub_f32_e32 v188, v188, v192
	v_sub_f32_e32 v189, v189, v192
	v_sub_f32_e32 v190, v190, v192
	v_sub_f32_e32 v191, v191, v192
	v_pk_mul_f32 v[184:185], v[192:193], v[184:185] op_sel:[1,0]
	v_pk_mul_f32 v[186:187], v[192:193], v[186:187] op_sel:[1,0]
	v_pk_mul_f32 v[188:189], v[192:193], v[188:189] op_sel:[1,0]
	v_pk_mul_f32 v[190:191], v[192:193], v[190:191] op_sel:[1,0]
	v_pk_fma_f32 v[184:185], v[136:137], v[184:185], v[132:133]
	v_pk_fma_f32 v[186:187], v[138:139], v[186:187], v[134:135]
	v_pk_fma_f32 v[188:189], v[128:129], v[188:189], v[140:141]
	v_pk_fma_f32 v[190:191], v[130:131], v[190:191], v[142:143]
	v_pk_fma_f32 v[64:65], v[184:185], s[14:15], v[64:65] op_sel_hi:[1,0,1]
	v_pk_fma_f32 v[66:67], v[186:187], s[14:15], v[66:67] op_sel_hi:[1,0,1]
	v_pk_fma_f32 v[56:57], v[188:189], s[14:15], v[56:57] op_sel_hi:[1,0,1]
	v_pk_fma_f32 v[58:59], v[190:191], s[14:15], v[58:59] op_sel_hi:[1,0,1]
	global_store_dwordx4 v[218:219], v[64:67], off
	global_store_dwordx4 v[218:219], v[56:59], off offset:16
	v_lshl_add_u64 v[218:219], v[218:219], 0, s[98:99]
	global_load_dwordx2 v[192:193], v[168:169], off offset:384
	global_load_dwordx4 v[184:187], v[216:217], off
	global_load_dwordx4 v[188:191], v[216:217], off offset:16
	v_lshl_add_u64 v[216:217], v[216:217], 0, s[100:101]
	s_waitcnt vmcnt(5)
	v_sub_f32_e32 v232, v232, v240
	v_sub_f32_e32 v233, v233, v240
	v_sub_f32_e32 v234, v234, v240
	v_sub_f32_e32 v235, v235, v240
	v_sub_f32_e32 v236, v236, v240
	v_sub_f32_e32 v237, v237, v240
	v_sub_f32_e32 v238, v238, v240
	v_sub_f32_e32 v239, v239, v240
	v_pk_mul_f32 v[232:233], v[240:241], v[232:233] op_sel:[1,0]
	v_pk_mul_f32 v[234:235], v[240:241], v[234:235] op_sel:[1,0]
	v_pk_mul_f32 v[236:237], v[240:241], v[236:237] op_sel:[1,0]
	v_pk_mul_f32 v[238:239], v[240:241], v[238:239] op_sel:[1,0]
	v_pk_fma_f32 v[232:233], v[136:137], v[232:233], v[132:133]
	v_pk_fma_f32 v[234:235], v[138:139], v[234:235], v[134:135]
	v_pk_fma_f32 v[236:237], v[128:129], v[236:237], v[140:141]
	v_pk_fma_f32 v[238:239], v[130:131], v[238:239], v[142:143]
	v_pk_fma_f32 v[52:53], v[232:233], s[14:15], v[52:53] op_sel_hi:[1,0,1]
	v_pk_fma_f32 v[54:55], v[234:235], s[14:15], v[54:55] op_sel_hi:[1,0,1]
	v_pk_fma_f32 v[48:49], v[236:237], s[14:15], v[48:49] op_sel_hi:[1,0,1]
	v_pk_fma_f32 v[50:51], v[238:239], s[14:15], v[50:51] op_sel_hi:[1,0,1]
	global_store_dwordx4 v[218:219], v[52:55], off
	global_store_dwordx4 v[218:219], v[48:51], off offset:16
	v_lshl_add_u64 v[218:219], v[218:219], 0, s[98:99]
	global_load_dwordx2 v[240:241], v[168:169], off offset:1024
	global_load_dwordx4 v[232:235], v[216:217], off
	global_load_dwordx4 v[236:239], v[216:217], off offset:16
	v_lshl_add_u64 v[216:217], v[216:217], 0, s[98:99]
	s_waitcnt vmcnt(10)
;     __device__ __forceinline__ void operator()(const f32x4 (&acc)[2][2][4][2], const Unit& u, int wr, int wc, int fr, int fq) const {
;     ...
;                 for (int m = 0; m < 4; ++m) { const int row = row0 + ai * HALF + m * 16; const size_t p = (size_t)row * ldc + col0 + bj * HALF;
;                     const float mean = stats[2 * row], rstd = stats[2 * row + 1];
;                     const f32x4 r0 = *(const f32x4*)(res + p), r1 = *(const f32x4*)(res + p + 4);
;                     const f32x4 n0 = (r0 - mean) * rstd * g0 + b0, n1 = (r1 - mean) * rstd * g1 + b1;
;                     *(f32x4*)(out + p) = n0 * alpha + acc[ai][bj][m][0]; *(f32x4*)(out + p + 4) = n1 * alpha + acc[ai][bj][m][1]; }
	v_sub_f32_e32 v244, v244, v242
	v_sub_f32_e32 v245, v245, v242
	v_sub_f32_e32 v246, v246, v242
	v_sub_f32_e32 v247, v247, v242
	v_sub_f32_e32 v248, v248, v242
	v_sub_f32_e32 v249, v249, v242
	v_sub_f32_e32 v250, v250, v242
	v_sub_f32_e32 v251, v251, v242
	v_pk_mul_f32 v[244:245], v[242:243], v[244:245] op_sel:[1,0]
	v_pk_mul_f32 v[246:247], v[242:243], v[246:247] op_sel:[1,0]
	v_pk_mul_f32 v[248:249], v[242:243], v[248:249] op_sel:[1,0]
	v_pk_mul_f32 v[250:251], v[242:243], v[250:251] op_sel:[1,0]
	v_pk_fma_f32 v[244:245], v[136:137], v[244:245], v[132:133]
	v_pk_fma_f32 v[246:247], v[138:139], v[246:247], v[134:135]
	v_pk_fma_f32 v[248:249], v[128:129], v[248:249], v[140:141]
	v_pk_fma_f32 v[250:251], v[130:131], v[250:251], v[142:143]
	v_pk_fma_f32 v[44:45], v[244:245], s[14:15], v[44:45] op_sel_hi:[1,0,1]
	v_pk_fma_f32 v[46:47], v[246:247], s[14:15], v[46:47] op_sel_hi:[1,0,1]
	v_pk_fma_f32 v[40:41], v[248:249], s[14:15], v[40:41] op_sel_hi:[1,0,1]
	v_pk_fma_f32 v[42:43], v[250:251], s[14:15], v[42:43] op_sel_hi:[1,0,1]
	global_store_dwordx4 v[218:219], v[44:47], off
	global_store_dwordx4 v[218:219], v[40:43], off offset:16
	v_lshl_add_u64 v[218:219], v[218:219], 0, s[98:99]
	global_load_dwordx2 v[242:243], v[168:169], off offset:1152
	global_load_dwordx4 v[244:247], v[216:217], off
	global_load_dwordx4 v[248:251], v[216:217], off offset:16
	v_lshl_add_u64 v[216:217], v[216:217], 0, s[98:99]
	s_waitcnt vmcnt(10)
	v_sub_f32_e32 v184, v184, v192
	v_sub_f32_e32 v185, v185, v192
	v_sub_f32_e32 v186, v186, v192
	v_sub_f32_e32 v187, v187, v192
	v_sub_f32_e32 v188, v188, v192
	v_sub_f32_e32 v189, v189, v192
	v_sub_f32_e32 v190, v190, v192
	v_sub_f32_e32 v191, v191, v192
	v_pk_mul_f32 v[184:185], v[192:193], v[184:185] op_sel:[1,0]
	v_pk_mul_f32 v[186:187], v[192:193], v[186:187] op_sel:[1,0]
	v_pk_mul_f32 v[188:189], v[192:193], v[188:189] op_sel:[1,0]
	v_pk_mul_f32 v[190:191], v[192:193], v[190:191] op_sel:[1,0]
	v_pk_fma_f32 v[184:185], v[136:137], v[184:185], v[132:133]
	v_pk_fma_f32 v[186:187], v[138:139], v[186:187], v[134:135]
	v_pk_fma_f32 v[188:189], v[128:129], v[188:189], v[140:141]
	v_pk_fma_f32 v[190:191], v[130:131], v[190:191], v[142:143]
	v_pk_fma_f32 v[36:37], v[184:185], s[14:15], v[36:37] op_sel_hi:[1,0,1]
	v_pk_fma_f32 v[38:39], v[186:187], s[14:15], v[38:39] op_sel_hi:[1,0,1]
	v_pk_fma_f32 v[32:33], v[188:189], s[14:15], v[32:33] op_sel_hi:[1,0,1]
	v_pk_fma_f32 v[34:35], v[190:191], s[14:15], v[34:35] op_sel_hi:[1,0,1]
	global_store_dwordx4 v[218:219], v[36:39], off
	global_store_dwordx4 v[218:219], v[32:35], off offset:16
	v_lshl_add_u64 v[218:219], v[218:219], 0, s[100:101]
	global_load_dwordx2 v[192:193], v[168:169], off offset:1280
	global_load_dwordx4 v[184:187], v[216:217], off
	global_load_dwordx4 v[188:191], v[216:217], off offset:16
	v_lshl_add_u64 v[216:217], v[216:217], 0, s[98:99]
	s_waitcnt vmcnt(10)
	v_sub_f32_e32 v232, v232, v240
	v_sub_f32_e32 v233, v233, v240
	v_sub_f32_e32 v234, v234, v240
	v_sub_f32_e32 v235, v235, v240
	v_sub_f32_e32 v236, v236, v240
	v_sub_f32_e32 v237, v237, v240
	v_sub_f32_e32 v238, v238, v240
	v_sub_f32_e32 v239, v239, v240
	v_pk_mul_f32 v[232:233], v[240:241], v[232:233] op_sel:[1,0]
	v_pk_mul_f32 v[234:235], v[240:241], v[234:235] op_sel:[1,0]
	v_pk_mul_f32 v[236:237], v[240:241], v[236:237] op_sel:[1,0]
	v_pk_mul_f32 v[238:239], v[240:241], v[238:239] op_sel:[1,0]
	v_pk_fma_f32 v[232:233], v[136:137], v[232:233], v[132:133]
	v_pk_fma_f32 v[234:235], v[138:139], v[234:235], v[134:135]
	v_pk_fma_f32 v[236:237], v[128:129], v[236:237], v[140:141]
	v_pk_fma_f32 v[238:239], v[130:131], v[238:239], v[142:143]
	v_pk_fma_f32 v[28:29], v[232:233], s[14:15], v[28:29] op_sel_hi:[1,0,1]
	v_pk_fma_f32 v[30:31], v[234:235], s[14:15], v[30:31] op_sel_hi:[1,0,1]
	v_pk_fma_f32 v[24:25], v[236:237], s[14:15], v[24:25] op_sel_hi:[1,0,1]
	v_pk_fma_f32 v[26:27], v[238:239], s[14:15], v[26:27] op_sel_hi:[1,0,1]
	global_store_dwordx4 v[218:219], v[28:31], off
	global_store_dwordx4 v[218:219], v[24:27], off offset:16
	v_lshl_add_u64 v[218:219], v[218:219], 0, s[98:99]
	global_load_dwordx2 v[240:241], v[168:169], off offset:1408
	global_load_dwordx4 v[232:235], v[216:217], off
	global_load_dwordx4 v[236:239], v[216:217], off offset:16
	s_waitcnt vmcnt(10)
;     __device__ __forceinline__ void operator()(const f32x4 (&acc)[2][2][4][2], const Unit& u, int wr, int wc, int fr, int fq) const {
;     ...
;                 for (int m = 0; m < 4; ++m) { const int row = row0 + ai * HALF + m * 16; const size_t p = (size_t)row * ldc + col0 + bj * HALF;
;                     const float mean = stats[2 * row], rstd = stats[2 * row + 1];
;                     const f32x4 r0 = *(const f32x4*)(res + p), r1 = *(const f32x4*)(res + p + 4);
;                     const f32x4 n0 = (r0 - mean) * rstd * g0 + b0, n1 = (r1 - mean) * rstd * g1 + b1;
;                     *(f32x4*)(out + p) = n0 * alpha + acc[ai][bj][m][0]; *(f32x4*)(out + p + 4) = n1 * alpha + acc[ai][bj][m][1]; }
	v_sub_f32_e32 v244, v244, v242
	v_sub_f32_e32 v245, v245, v242
	v_sub_f32_e32 v246, v246, v242
	v_sub_f32_e32 v247, v247, v242
	v_sub_f32_e32 v248, v248, v242
	v_sub_f32_e32 v249, v249, v242
	v_sub_f32_e32 v250, v250, v242
	v_sub_f32_e32 v251, v251, v242
	v_pk_mul_f32 v[244:245], v[242:243], v[244:245] op_sel:[1,0]
	v_pk_mul_f32 v[246:247], v[242:243], v[246:247] op_sel:[1,0]
	v_pk_mul_f32 v[248:249], v[242:243], v[248:249] op_sel:[1,0]
	v_pk_mul_f32 v[250:251], v[242:243], v[250:251] op_sel:[1,0]
	v_pk_fma_f32 v[244:245], v[136:137], v[244:245], v[132:133]
	v_pk_fma_f32 v[246:247], v[138:139], v[246:247], v[134:135]
	v_pk_fma_f32 v[248:249], v[128:129], v[248:249], v[140:141]
	v_pk_fma_f32 v[250:251], v[130:131], v[250:251], v[142:143]
	v_pk_fma_f32 v[20:21], v[244:245], s[14:15], v[20:21] op_sel_hi:[1,0,1]
	v_pk_fma_f32 v[22:23], v[246:247], s[14:15], v[22:23] op_sel_hi:[1,0,1]
	v_pk_fma_f32 v[16:17], v[248:249], s[14:15], v[16:17] op_sel_hi:[1,0,1]
	v_pk_fma_f32 v[18:19], v[250:251], s[14:15], v[18:19] op_sel_hi:[1,0,1]
	global_store_dwordx4 v[218:219], v[20:23], off
	global_store_dwordx4 v[218:219], v[16:19], off offset:16
	v_lshl_add_u64 v[218:219], v[218:219], 0, s[98:99]
	s_waitcnt vmcnt(7)
	v_sub_f32_e32 v184, v184, v192
	v_sub_f32_e32 v185, v185, v192
	v_sub_f32_e32 v186, v186, v192
	v_sub_f32_e32 v187, v187, v192
	v_sub_f32_e32 v188, v188, v192
	v_sub_f32_e32 v189, v189, v192
	v_sub_f32_e32 v190, v190, v192
	v_sub_f32_e32 v191, v191, v192
	v_pk_mul_f32 v[184:185], v[192:193], v[184:185] op_sel:[1,0]
	v_pk_mul_f32 v[186:187], v[192:193], v[186:187] op_sel:[1,0]
	v_pk_mul_f32 v[188:189], v[192:193], v[188:189] op_sel:[1,0]
	v_pk_mul_f32 v[190:191], v[192:193], v[190:191] op_sel:[1,0]
	v_pk_fma_f32 v[184:185], v[136:137], v[184:185], v[132:133]
	v_pk_fma_f32 v[186:187], v[138:139], v[186:187], v[134:135]
	v_pk_fma_f32 v[188:189], v[128:129], v[188:189], v[140:141]
	v_pk_fma_f32 v[190:191], v[130:131], v[190:191], v[142:143]
	v_pk_fma_f32 v[12:13], v[184:185], s[14:15], v[12:13] op_sel_hi:[1,0,1]
	v_pk_fma_f32 v[14:15], v[186:187], s[14:15], v[14:15] op_sel_hi:[1,0,1]
	v_pk_fma_f32 v[8:9], v[188:189], s[14:15], v[8:9] op_sel_hi:[1,0,1]
	v_pk_fma_f32 v[10:11], v[190:191], s[14:15], v[10:11] op_sel_hi:[1,0,1]
	global_store_dwordx4 v[218:219], v[12:15], off
	global_store_dwordx4 v[218:219], v[8:11], off offset:16
	v_lshl_add_u64 v[218:219], v[218:219], 0, s[98:99]
	s_waitcnt vmcnt(4)
	v_sub_f32_e32 v232, v232, v240
	v_sub_f32_e32 v233, v233, v240
	v_sub_f32_e32 v234, v234, v240
	v_sub_f32_e32 v235, v235, v240
	v_sub_f32_e32 v236, v236, v240
	v_sub_f32_e32 v237, v237, v240
	v_sub_f32_e32 v238, v238, v240
	v_sub_f32_e32 v239, v239, v240
	v_pk_mul_f32 v[232:233], v[240:241], v[232:233] op_sel:[1,0]
	v_pk_mul_f32 v[234:235], v[240:241], v[234:235] op_sel:[1,0]
	v_pk_mul_f32 v[236:237], v[240:241], v[236:237] op_sel:[1,0]
	v_pk_mul_f32 v[238:239], v[240:241], v[238:239] op_sel:[1,0]
	v_pk_fma_f32 v[232:233], v[136:137], v[232:233], v[132:133]
	v_pk_fma_f32 v[234:235], v[138:139], v[234:235], v[134:135]
	v_pk_fma_f32 v[236:237], v[128:129], v[236:237], v[140:141]
	v_pk_fma_f32 v[238:239], v[130:131], v[238:239], v[142:143]
	v_pk_fma_f32 v[4:5], v[232:233], s[14:15], v[4:5] op_sel_hi:[1,0,1]
	v_pk_fma_f32 v[6:7], v[234:235], s[14:15], v[6:7] op_sel_hi:[1,0,1]
	v_pk_fma_f32 v[0:1], v[236:237], s[14:15], v[0:1] op_sel_hi:[1,0,1]
	v_pk_fma_f32 v[2:3], v[238:239], s[14:15], v[2:3] op_sel_hi:[1,0,1]
	global_store_dwordx4 v[218:219], v[4:7], off
	global_store_dwordx4 v[218:219], v[0:3], off offset:16
	s_cbranch_vccnz .LBB0_1261
	s_andn2_b64 vcc, exec, s[6:7]
	s_cbranch_vccnz .LBB0_1260
	s_barrier
	s_branch .LBB0_1260

;     __device__ __forceinline__ void operator()(const f32x4 (&acc)[2][2][4][2], const Unit& u, int wr, int wc, int fr, int fq) const {
;         const int row0 = u.pm * BM + wr * 64 + fr; const int col0 = u.pn * BM + wc * 32 + 8 * fq;
; #pragma unroll
;         for (int bj = 0; bj < 2; ++bj) {
;             const f32x4 g0 = *(const f32x4*)(g + col0 + bj * HALF), g1 = *(const f32x4*)(g + col0 + bj * HALF + 4);
;             const f32x4 b0 = *(const f32x4*)(b + col0 + bj * HALF), b1 = *(const f32x4*)(b + col0 + bj * HALF + 4);
; #pragma unroll
;             for (int ai = 0; ai < 2; ++ai)
; #pragma unroll
;                 for (int m = 0; m < 4; ++m) { const int row = row0 + ai * HALF + m * 16; const size_t p = (size_t)row * ldc + col0 + bj * HALF;
;                     const float mean = stats[2 * row], rstd = stats[2 * row + 1];
;                     const f32x4 r0 = *(const f32x4*)(res + p), r1 = *(const f32x4*)(res + p + 4);
;                     const f32x4 n0 = (r0 - mean) * rstd * g0 + b0, n1 = (r1 - mean) * rstd * g1 + b1;
;                     *(f32x4*)(out + p) = n0 * alpha + acc[ai][bj][m][0]; *(f32x4*)(out + p + 4) = n1 * alpha + acc[ai][bj][m][1]; }
.LBB0_1472:
	v_lshl_or_b32 v128, s53, 8, v180
	v_lshl_add_u32 v178, s38, 8, v145
	v_ashrrev_i32_e32 v129, 31, v128
	v_lshlrev_b64 v[176:177], 2, v[128:129]
	v_lshlrev_b32_e32 v128, 1, v178
	v_ashrrev_i32_e32 v179, 31, v178
	v_ashrrev_i32_e32 v129, 31, v128
	v_lshl_add_u64 v[168:169], v[128:129], 2, s[12:13]
	v_lshlrev_b64 v[128:129], 13, v[178:179]
	v_lshl_add_u64 v[128:129], s[20:21], 0, v[128:129]
	v_lshl_add_u64 v[164:165], v[128:129], 0, v[176:177]
	v_lshl_add_u64 v[172:173], s[10:11], 0, v[176:177]
	v_lshl_add_u64 v[170:171], s[8:9], 0, v[176:177]
	v_or_b32_e32 v166, 16, v178
	v_ashrrev_i32_e32 v167, 31, v166
	v_lshlrev_b32_e32 v174, 1, v166
	v_ashrrev_i32_e32 v175, 31, v174
	v_lshlrev_b64 v[166:167], 13, v[166:167]
	v_lshl_add_u64 v[174:175], v[174:175], 2, s[12:13]
	v_lshl_add_u64 v[166:167], s[20:21], 0, v[166:167]
	v_lshl_add_u64 v[166:167], v[166:167], 0, v[176:177]
	s_andn2_b64 vcc, exec, s[0:1]
	s_mov_b64 s[0:1], -1
	v_mov_b64_e32 v[216:217], v[164:165]
	v_mov_b64_e32 v[218:219], v[164:165]
	s_mov_b64 s[98:99], 0x20000
	s_mov_b64 s[100:101], 0xa0000
	v_mov_b32_e32 v220, 0x200
	v_mov_b32_e32 v221, 0
	global_load_dwordx4 v[128:131], v[170:171], off offset:16
	global_load_dwordx4 v[132:135], v[172:173], off
	global_load_dwordx4 v[136:139], v[170:171], off
	global_load_dwordx4 v[140:143], v[172:173], off offset:16
	global_load_dwordx2 v[240:241], v[168:169], off
	global_load_dwordx4 v[232:235], v[216:217], off
	global_load_dwordx4 v[236:239], v[216:217], off offset:16
	v_lshl_add_u64 v[216:217], v[216:217], 0, s[98:99]
	global_load_dwordx2 v[242:243], v[168:169], off offset:128
	global_load_dwordx4 v[244:247], v[216:217], off
	global_load_dwordx4 v[248:251], v[216:217], off offset:16
	v_lshl_add_u64 v[216:217], v[216:217], 0, s[98:99]
	global_load_dwordx2 v[192:193], v[168:169], off offset:256
	global_load_dwordx4 v[184:187], v[216:217], off
	global_load_dwordx4 v[188:191], v[216:217], off offset:16
	v_lshl_add_u64 v[216:217], v[216:217], 0, s[98:99]
	s_waitcnt vmcnt(6)
	v_sub_f32_e32 v232, v232, v240
	v_sub_f32_e32 v233, v233, v240
	v_sub_f32_e32 v234, v234, v240
	v_sub_f32_e32 v235, v235, v240
	v_sub_f32_e32 v236, v236, v240
	v_sub_f32_e32 v237, v237, v240
	v_sub_f32_e32 v238, v238, v240
	v_sub_f32_e32 v239, v239, v240
	v_pk_mul_f32 v[232:233], v[240:241], v[232:233] op_sel:[1,0]
	v_pk_mul_f32 v[234:235], v[240:241], v[234:235] op_sel:[1,0]
	v_pk_mul_f32 v[236:237], v[240:241], v[236:237] op_sel:[1,0]
	v_pk_mul_f32 v[238:239], v[240:241], v[238:239] op_sel:[1,0]
	v_pk_fma_f32 v[232:233], v[136:137], v[232:233], v[132:133]
	v_pk_fma_f32 v[234:235], v[138:139], v[234:235], v[134:135]
	v_pk_fma_f32 v[236:237], v[128:129], v[236:237], v[140:141]
	v_pk_fma_f32 v[238:239], v[130:131], v[238:239], v[142:143]
	v_pk_fma_f32 v[124:125], v[232:233], s[26:27], v[124:125] op_sel_hi:[1,0,1]
	v_pk_fma_f32 v[126:127], v[234:235], s[26:27], v[126:127] op_sel_hi:[1,0,1]
	v_pk_fma_f32 v[120:121], v[236:237], s[26:27], v[120:121] op_sel_hi:[1,0,1]
	v_pk_fma_f32 v[122:123], v[238:239], s[26:27], v[122:123] op_sel_hi:[1,0,1]
	global_store_dwordx4 v[218:219], v[124:127], off
	global_store_dwordx4 v[218:219], v[120:123], off offset:16
	v_lshl_add_u64 v[218:219], v[218:219], 0, s[98:99]
	global_load_dwordx2 v[240:241], v[168:169], off offset:384
	global_load_dwordx4 v[232:235], v[216:217], off
	global_load_dwordx4 v[236:239], v[216:217], off offset:16
	v_lshl_add_u64 v[216:217], v[216:217], 0, s[100:101]
	s_waitcnt vmcnt(8)
	v_sub_f32_e32 v244, v244, v242
	v_sub_f32_e32 v245, v245, v242
	v_sub_f32_e32 v246, v246, v242
	v_sub_f32_e32 v247, v247, v242
	v_sub_f32_e32 v248, v248, v242
	v_sub_f32_e32 v249, v249, v242
	v_sub_f32_e32 v250, v250, v242
	v_sub_f32_e32 v251, v251, v242
	v_pk_mul_f32 v[244:245], v[242:243], v[244:245] op_sel:[1,0]
	v_pk_mul_f32 v[246:247], v[242:243], v[246:247] op_sel:[1,0]
	v_pk_mul_f32 v[248:249], v[242:243], v[248:249] op_sel:[1,0]
	v_pk_mul_f32 v[250:251], v[242:243], v[250:251] op_sel:[1,0]
	v_pk_fma_f32 v[244:245], v[136:137], v[244:245], v[132:133]
	v_pk_fma_f32 v[246:247], v[138:139], v[246:247], v[134:135]
	v_pk_fma_f32 v[248:249], v[128:129], v[248:249], v[140:141]
	v_pk_fma_f32 v[250:251], v[130:131], v[250:251], v[142:143]
	v_pk_fma_f32 v[116:117], v[244:245], s[26:27], v[116:117] op_sel_hi:[1,0,1]
	v_pk_fma_f32 v[118:119], v[246:247], s[26:27], v[118:119] op_sel_hi:[1,0,1]
	v_pk_fma_f32 v[112:113], v[248:249], s[26:27], v[112:113] op_sel_hi:[1,0,1]
	v_pk_fma_f32 v[114:115], v[250:251], s[26:27], v[114:115] op_sel_hi:[1,0,1]
	global_store_dwordx4 v[218:219], v[116:119], off
	global_store_dwordx4 v[218:219], v[112:115], off offset:16
	v_lshl_add_u64 v[218:219], v[218:219], 0, s[98:99]
	global_load_dwordx2 v[242:243], v[168:169], off offset:1024
	global_load_dwordx4 v[244:247], v[216:217], off
	global_load_dwordx4 v[248:251], v[216:217], off offset:16
	v_lshl_add_u64 v[216:217], v[216:217], 0, s[98:99]
	s_waitcnt vmcnt(10)
;     __device__ __forceinline__ void operator()(const f32x4 (&acc)[2][2][4][2], const Unit& u, int wr, int wc, int fr, int fq) const {
;     ...
;                 for (int m = 0; m < 4; ++m) { const int row = row0 + ai * HALF + m * 16; const size_t p = (size_t)row * ldc + col0 + bj * HALF;
;                     const float mean = stats[2 * row], rstd = stats[2 * row + 1];
;                     const f32x4 r0 = *(const f32x4*)(res + p), r1 = *(const f32x4*)(res + p + 4);
;                     const f32x4 n0 = (r0 - mean) * rstd * g0 + b0, n1 = (r1 - mean) * rstd * g1 + b1;
;                     *(f32x4*)(out + p) = n0 * alpha + acc[ai][bj][m][0]; *(f32x4*)(out + p + 4) = n1 * alpha + acc[ai][bj][m][1]; }
	v_sub_f32_e32 v184, v184, v192
	v_sub_f32_e32 v185, v185, v192
	v_sub_f32_e32 v186, v186, v192
	v_sub_f32_e32 v187, v187, v192
	v_sub_f32_e32 v188, v188, v192
	v_sub_f32_e32 v189, v189, v192
	v_sub_f32_e32 v190, v190, v192
	v_sub_f32_e32 v191, v191, v192
	v_pk_mul_f32 v[184:185], v[192:193], v[184:185] op_sel:[1,0]
	v_pk_mul_f32 v[186:187], v[192:193], v[186:187] op_sel:[1,0]
	v_pk_mul_f32 v[188:189], v[192:193], v[188:189] op_sel:[1,0]
	v_pk_mul_f32 v[190:191], v[192:193], v[190:191] op_sel:[1,0]
	v_pk_fma_f32 v[184:185], v[136:137], v[184:185], v[132:133]
	v_pk_fma_f32 v[186:187], v[138:139], v[186:187], v[134:135]
	v_pk_fma_f32 v[188:189], v[128:129], v[188:189], v[140:141]
	v_pk_fma_f32 v[190:191], v[130:131], v[190:191], v[142:143]
	v_pk_fma_f32 v[108:109], v[184:185], s[26:27], v[108:109] op_sel_hi:[1,0,1]
	v_pk_fma_f32 v[110:111], v[186:187], s[26:27], v[110:111] op_sel_hi:[1,0,1]
	v_pk_fma_f32 v[104:105], v[188:189], s[26:27], v[104:105] op_sel_hi:[1,0,1]
	v_pk_fma_f32 v[106:107], v[190:191], s[26:27], v[106:107] op_sel_hi:[1,0,1]
	global_store_dwordx4 v[218:219], v[108:111], off
	global_store_dwordx4 v[218:219], v[104:107], off offset:16
	v_lshl_add_u64 v[218:219], v[218:219], 0, s[98:99]
	global_load_dwordx2 v[192:193], v[168:169], off offset:1152
	global_load_dwordx4 v[184:187], v[216:217], off
	global_load_dwordx4 v[188:191], v[216:217], off offset:16
	v_lshl_add_u64 v[216:217], v[216:217], 0, s[98:99]
	s_waitcnt vmcnt(10)
	v_sub_f32_e32 v232, v232, v240
	v_sub_f32_e32 v233, v233, v240
	v_sub_f32_e32 v234, v234, v240
	v_sub_f32_e32 v235, v235, v240
	v_sub_f32_e32 v236, v236, v240
	v_sub_f32_e32 v237, v237, v240
	v_sub_f32_e32 v238, v238, v240
	v_sub_f32_e32 v239, v239, v240
	v_pk_mul_f32 v[232:233], v[240:241], v[232:233] op_sel:[1,0]
	v_pk_mul_f32 v[234:235], v[240:241], v[234:235] op_sel:[1,0]
	v_pk_mul_f32 v[236:237], v[240:241], v[236:237] op_sel:[1,0]
	v_pk_mul_f32 v[238:239], v[240:241], v[238:239] op_sel:[1,0]
	v_pk_fma_f32 v[232:233], v[136:137], v[232:233], v[132:133]
	v_pk_fma_f32 v[234:235], v[138:139], v[234:235], v[134:135]
	v_pk_fma_f32 v[236:237], v[128:129], v[236:237], v[140:141]
	v_pk_fma_f32 v[238:239], v[130:131], v[238:239], v[142:143]
	v_pk_fma_f32 v[100:101], v[232:233], s[26:27], v[100:101] op_sel_hi:[1,0,1]
	v_pk_fma_f32 v[102:103], v[234:235], s[26:27], v[102:103] op_sel_hi:[1,0,1]
	v_pk_fma_f32 v[96:97], v[236:237], s[26:27], v[96:97] op_sel_hi:[1,0,1]
	v_pk_fma_f32 v[98:99], v[238:239], s[26:27], v[98:99] op_sel_hi:[1,0,1]
	global_store_dwordx4 v[218:219], v[100:103], off
	global_store_dwordx4 v[218:219], v[96:99], off offset:16
	v_lshl_add_u64 v[218:219], v[218:219], 0, s[100:101]
	global_load_dwordx2 v[240:241], v[168:169], off offset:1280
	global_load_dwordx4 v[232:235], v[216:217], off
	global_load_dwordx4 v[236:239], v[216:217], off offset:16
	v_lshl_add_u64 v[216:217], v[216:217], 0, s[98:99]
	s_waitcnt vmcnt(10)
	v_sub_f32_e32 v244, v244, v242
	v_sub_f32_e32 v245, v245, v242
	v_sub_f32_e32 v246, v246, v242
	v_sub_f32_e32 v247, v247, v242
	v_sub_f32_e32 v248, v248, v242
	v_sub_f32_e32 v249, v249, v242
	v_sub_f32_e32 v250, v250, v242
	v_sub_f32_e32 v251, v251, v242
	v_pk_mul_f32 v[244:245], v[242:243], v[244:245] op_sel:[1,0]
	v_pk_mul_f32 v[246:247], v[242:243], v[246:247] op_sel:[1,0]
	v_pk_mul_f32 v[248:249], v[242:243], v[248:249] op_sel:[1,0]
	v_pk_mul_f32 v[250:251], v[242:243], v[250:251] op_sel:[1,0]
	v_pk_fma_f32 v[244:245], v[136:137], v[244:245], v[132:133]
	v_pk_fma_f32 v[246:247], v[138:139], v[246:247], v[134:135]
	v_pk_fma_f32 v[248:249], v[128:129], v[248:249], v[140:141]
	v_pk_fma_f32 v[250:251], v[130:131], v[250:251], v[142:143]
	v_pk_fma_f32 v[92:93], v[244:245], s[26:27], v[92:93] op_sel_hi:[1,0,1]
	v_pk_fma_f32 v[94:95], v[246:247], s[26:27], v[94:95] op_sel_hi:[1,0,1]
	v_pk_fma_f32 v[88:89], v[248:249], s[26:27], v[88:89] op_sel_hi:[1,0,1]
	v_pk_fma_f32 v[90:91], v[250:251], s[26:27], v[90:91] op_sel_hi:[1,0,1]
	global_store_dwordx4 v[218:219], v[92:95], off
	global_store_dwordx4 v[218:219], v[88:91], off offset:16
	v_lshl_add_u64 v[218:219], v[218:219], 0, s[98:99]
	global_load_dwordx2 v[242:243], v[168:169], off offset:1408
	global_load_dwordx4 v[244:247], v[216:217], off
	global_load_dwordx4 v[248:251], v[216:217], off offset:16
	v_lshl_add_u64 v[216:217], v[220:221], 0, v[164:165]
	s_waitcnt vmcnt(10)
	v_sub_f32_e32 v184, v184, v192
	v_sub_f32_e32 v185, v185, v192
	v_sub_f32_e32 v186, v186, v192
	v_sub_f32_e32 v187, v187, v192
	v_sub_f32_e32 v188, v188, v192
	v_sub_f32_e32 v189, v189, v192
	v_sub_f32_e32 v190, v190, v192
	v_sub_f32_e32 v191, v191, v192
	v_pk_mul_f32 v[184:185], v[192:193], v[184:185] op_sel:[1,0]
	v_pk_mul_f32 v[186:187], v[192:193], v[186:187] op_sel:[1,0]
	v_pk_mul_f32 v[188:189], v[192:193], v[188:189] op_sel:[1,0]
	v_pk_mul_f32 v[190:191], v[192:193], v[190:191] op_sel:[1,0]
	v_pk_fma_f32 v[184:185], v[136:137], v[184:185], v[132:133]
	v_pk_fma_f32 v[186:187], v[138:139], v[186:187], v[134:135]
	v_pk_fma_f32 v[188:189], v[128:129], v[188:189], v[140:141]
	v_pk_fma_f32 v[190:191], v[130:131], v[190:191], v[142:143]
	v_pk_fma_f32 v[84:85], v[184:185], s[26:27], v[84:85] op_sel_hi:[1,0,1]
	v_pk_fma_f32 v[86:87], v[186:187], s[26:27], v[86:87] op_sel_hi:[1,0,1]
	v_pk_fma_f32 v[80:81], v[188:189], s[26:27], v[80:81] op_sel_hi:[1,0,1]
	v_pk_fma_f32 v[82:83], v[190:191], s[26:27], v[82:83] op_sel_hi:[1,0,1]
	global_store_dwordx4 v[218:219], v[84:87], off
	global_store_dwordx4 v[218:219], v[80:83], off offset:16
	v_lshl_add_u64 v[218:219], v[218:219], 0, s[98:99]
	global_load_dwordx2 v[192:193], v[168:169], off
	global_load_dwordx4 v[184:187], v[216:217], off
	global_load_dwordx4 v[188:191], v[216:217], off offset:16
	v_lshl_add_u64 v[216:217], v[216:217], 0, s[98:99]
	s_waitcnt vmcnt(10)
;     __device__ __forceinline__ void operator()(const f32x4 (&acc)[2][2][4][2], const Unit& u, int wr, int wc, int fr, int fq) const {
;     ...
;         for (int bj = 0; bj < 2; ++bj) {
;             const f32x4 g0 = *(const f32x4*)(g + col0 + bj * HALF), g1 = *(const f32x4*)(g + col0 + bj * HALF + 4);
;             const f32x4 b0 = *(const f32x4*)(b + col0 + bj * HALF), b1 = *(const f32x4*)(b + col0 + bj * HALF + 4);
; #pragma unroll
;             for (int ai = 0; ai < 2; ++ai)
; #pragma unroll
;                 for (int m = 0; m < 4; ++m) { const int row = row0 + ai * HALF + m * 16; const size_t p = (size_t)row * ldc + col0 + bj * HALF;
;                     const float mean = stats[2 * row], rstd = stats[2 * row + 1];
;                     const f32x4 r0 = *(const f32x4*)(res + p), r1 = *(const f32x4*)(res + p + 4);
;                     const f32x4 n0 = (r0 - mean) * rstd * g0 + b0, n1 = (r1 - mean) * rstd * g1 + b1;
;                     *(f32x4*)(out + p) = n0 * alpha + acc[ai][bj][m][0]; *(f32x4*)(out + p + 4) = n1 * alpha + acc[ai][bj][m][1]; }
	v_sub_f32_e32 v232, v232, v240
	v_sub_f32_e32 v233, v233, v240
	v_sub_f32_e32 v234, v234, v240
	v_sub_f32_e32 v235, v235, v240
	v_sub_f32_e32 v236, v236, v240
	v_sub_f32_e32 v237, v237, v240
	v_sub_f32_e32 v238, v238, v240
	v_sub_f32_e32 v239, v239, v240
	v_pk_mul_f32 v[232:233], v[240:241], v[232:233] op_sel:[1,0]
	v_pk_mul_f32 v[234:235], v[240:241], v[234:235] op_sel:[1,0]
	v_pk_mul_f32 v[236:237], v[240:241], v[236:237] op_sel:[1,0]
	v_pk_mul_f32 v[238:239], v[240:241], v[238:239] op_sel:[1,0]
	v_pk_fma_f32 v[232:233], v[136:137], v[232:233], v[132:133]
	v_pk_fma_f32 v[234:235], v[138:139], v[234:235], v[134:135]
	v_pk_fma_f32 v[236:237], v[128:129], v[236:237], v[140:141]
	v_pk_fma_f32 v[238:239], v[130:131], v[238:239], v[142:143]
	v_pk_fma_f32 v[76:77], v[232:233], s[26:27], v[76:77] op_sel_hi:[1,0,1]
	v_pk_fma_f32 v[78:79], v[234:235], s[26:27], v[78:79] op_sel_hi:[1,0,1]
	v_pk_fma_f32 v[72:73], v[236:237], s[26:27], v[72:73] op_sel_hi:[1,0,1]
	v_pk_fma_f32 v[74:75], v[238:239], s[26:27], v[74:75] op_sel_hi:[1,0,1]
	global_store_dwordx4 v[218:219], v[76:79], off
	global_store_dwordx4 v[218:219], v[72:75], off offset:16
	v_lshl_add_u64 v[218:219], v[218:219], 0, s[98:99]
	global_load_dwordx2 v[240:241], v[168:169], off offset:128
	global_load_dwordx4 v[232:235], v[216:217], off
	global_load_dwordx4 v[236:239], v[216:217], off offset:16
	v_lshl_add_u64 v[216:217], v[216:217], 0, s[98:99]
	s_waitcnt vmcnt(10)
	v_sub_f32_e32 v244, v244, v242
	v_sub_f32_e32 v245, v245, v242
	v_sub_f32_e32 v246, v246, v242
	v_sub_f32_e32 v247, v247, v242
	v_sub_f32_e32 v248, v248, v242
	v_sub_f32_e32 v249, v249, v242
	v_sub_f32_e32 v250, v250, v242
	v_sub_f32_e32 v251, v251, v242
	v_pk_mul_f32 v[244:245], v[242:243], v[244:245] op_sel:[1,0]
	v_pk_mul_f32 v[246:247], v[242:243], v[246:247] op_sel:[1,0]
	v_pk_mul_f32 v[248:249], v[242:243], v[248:249] op_sel:[1,0]
	v_pk_mul_f32 v[250:251], v[242:243], v[250:251] op_sel:[1,0]
	v_pk_fma_f32 v[244:245], v[136:137], v[244:245], v[132:133]
	v_pk_fma_f32 v[246:247], v[138:139], v[246:247], v[134:135]
	v_pk_fma_f32 v[248:249], v[128:129], v[248:249], v[140:141]
	v_pk_fma_f32 v[250:251], v[130:131], v[250:251], v[142:143]
	v_pk_fma_f32 v[68:69], v[244:245], s[26:27], v[68:69] op_sel_hi:[1,0,1]
	v_pk_fma_f32 v[70:71], v[246:247], s[26:27], v[70:71] op_sel_hi:[1,0,1]
	v_pk_fma_f32 v[60:61], v[248:249], s[26:27], v[60:61] op_sel_hi:[1,0,1]
	v_pk_fma_f32 v[62:63], v[250:251], s[26:27], v[62:63] op_sel_hi:[1,0,1]
	global_store_dwordx4 v[218:219], v[68:71], off
	global_store_dwordx4 v[218:219], v[60:63], off offset:16
	v_lshl_add_u64 v[218:219], v[220:221], 0, v[164:165]
	global_load_dwordx2 v[242:243], v[168:169], off offset:256
	global_load_dwordx4 v[244:247], v[216:217], off
	global_load_dwordx4 v[248:251], v[216:217], off offset:16
	v_lshl_add_u64 v[216:217], v[216:217], 0, s[98:99]
	global_load_dwordx4 v[128:131], v[170:171], off offset:528
	global_load_dwordx4 v[132:135], v[172:173], off offset:512
	global_load_dwordx4 v[136:139], v[170:171], off offset:512
	global_load_dwordx4 v[140:143], v[172:173], off offset:528
	s_waitcnt vmcnt(0)
	v_sub_f32_e32 v184, v184, v192
	v_sub_f32_e32 v185, v185, v192
	v_sub_f32_e32 v186, v186, v192
	v_sub_f32_e32 v187, v187, v192
	v_sub_f32_e32 v188, v188, v192
	v_sub_f32_e32 v189, v189, v192
	v_sub_f32_e32 v190, v190, v192
	v_sub_f32_e32 v191, v191, v192
	v_pk_mul_f32 v[184:185], v[192:193], v[184:185] op_sel:[1,0]
	v_pk_mul_f32 v[186:187], v[192:193], v[186:187] op_sel:[1,0]
	v_pk_mul_f32 v[188:189], v[192:193], v[188:189] op_sel:[1,0]
	v_pk_mul_f32 v[190:191], v[192:193], v[190:191] op_sel:[1,0]
	v_pk_fma_f32 v[184:185], v[136:137], v[184:185], v[132:133]
	v_pk_fma_f32 v[186:187], v[138:139], v[186:187], v[134:135]
	v_pk_fma_f32 v[188:189], v[128:129], v[188:189], v[140:141]
	v_pk_fma_f32 v[190:191], v[130:131], v[190:191], v[142:143]
	v_pk_fma_f32 v[64:65], v[184:185], s[26:27], v[64:65] op_sel_hi:[1,0,1]
	v_pk_fma_f32 v[66:67], v[186:187], s[26:27], v[66:67] op_sel_hi:[1,0,1]
	v_pk_fma_f32 v[56:57], v[188:189], s[26:27], v[56:57] op_sel_hi:[1,0,1]
	v_pk_fma_f32 v[58:59], v[190:191], s[26:27], v[58:59] op_sel_hi:[1,0,1]
	global_store_dwordx4 v[218:219], v[64:67], off
	global_store_dwordx4 v[218:219], v[56:59], off offset:16
	v_lshl_add_u64 v[218:219], v[218:219], 0, s[98:99]
	global_load_dwordx2 v[192:193], v[168:169], off offset:384
	global_load_dwordx4 v[184:187], v[216:217], off
	global_load_dwordx4 v[188:191], v[216:217], off offset:16
	v_lshl_add_u64 v[216:217], v[216:217], 0, s[100:101]
	s_waitcnt vmcnt(5)
	v_sub_f32_e32 v232, v232, v240
	v_sub_f32_e32 v233, v233, v240
	v_sub_f32_e32 v234, v234, v240
	v_sub_f32_e32 v235, v235, v240
	v_sub_f32_e32 v236, v236, v240
	v_sub_f32_e32 v237, v237, v240
	v_sub_f32_e32 v238, v238, v240
	v_sub_f32_e32 v239, v239, v240
	v_pk_mul_f32 v[232:233], v[240:241], v[232:233] op_sel:[1,0]
	v_pk_mul_f32 v[234:235], v[240:241], v[234:235] op_sel:[1,0]
	v_pk_mul_f32 v[236:237], v[240:241], v[236:237] op_sel:[1,0]
	v_pk_mul_f32 v[238:239], v[240:241], v[238:239] op_sel:[1,0]
	v_pk_fma_f32 v[232:233], v[136:137], v[232:233], v[132:133]
	v_pk_fma_f32 v[234:235], v[138:139], v[234:235], v[134:135]
	v_pk_fma_f32 v[236:237], v[128:129], v[236:237], v[140:141]
	v_pk_fma_f32 v[238:239], v[130:131], v[238:239], v[142:143]
	v_pk_fma_f32 v[52:53], v[232:233], s[26:27], v[52:53] op_sel_hi:[1,0,1]
	v_pk_fma_f32 v[54:55], v[234:235], s[26:27], v[54:55] op_sel_hi:[1,0,1]
	v_pk_fma_f32 v[48:49], v[236:237], s[26:27], v[48:49] op_sel_hi:[1,0,1]
	v_pk_fma_f32 v[50:51], v[238:239], s[26:27], v[50:51] op_sel_hi:[1,0,1]
	global_store_dwordx4 v[218:219], v[52:55], off
	global_store_dwordx4 v[218:219], v[48:51], off offset:16
	v_lshl_add_u64 v[218:219], v[218:219], 0, s[98:99]
	global_load_dwordx2 v[240:241], v[168:169], off offset:1024
	global_load_dwordx4 v[232:235], v[216:217], off
	global_load_dwordx4 v[236:239], v[216:217], off offset:16
	v_lshl_add_u64 v[216:217], v[216:217], 0, s[98:99]
	s_waitcnt vmcnt(10)
;     __device__ __forceinline__ void operator()(const f32x4 (&acc)[2][2][4][2], const Unit& u, int wr, int wc, int fr, int fq) const {
;     ...
;                 for (int m = 0; m < 4; ++m) { const int row = row0 + ai * HALF + m * 16; const size_t p = (size_t)row * ldc + col0 + bj * HALF;
;                     const float mean = stats[2 * row], rstd = stats[2 * row + 1];
;                     const f32x4 r0 = *(const f32x4*)(res + p), r1 = *(const f32x4*)(res + p + 4);
;                     const f32x4 n0 = (r0 - mean) * rstd * g0 + b0, n1 = (r1 - mean) * rstd * g1 + b1;
;                     *(f32x4*)(out + p) = n0 * alpha + acc[ai][bj][m][0]; *(f32x4*)(out + p + 4) = n1 * alpha + acc[ai][bj][m][1]; }
	v_sub_f32_e32 v244, v244, v242
	v_sub_f32_e32 v245, v245, v242
	v_sub_f32_e32 v246, v246, v242
	v_sub_f32_e32 v247, v247, v242
	v_sub_f32_e32 v248, v248, v242
	v_sub_f32_e32 v249, v249, v242
	v_sub_f32_e32 v250, v250, v242
	v_sub_f32_e32 v251, v251, v242
	v_pk_mul_f32 v[244:245], v[242:243], v[244:245] op_sel:[1,0]
	v_pk_mul_f32 v[246:247], v[242:243], v[246:247] op_sel:[1,0]
	v_pk_mul_f32 v[248:249], v[242:243], v[248:249] op_sel:[1,0]
	v_pk_mul_f32 v[250:251], v[242:243], v[250:251] op_sel:[1,0]
	v_pk_fma_f32 v[244:245], v[136:137], v[244:245], v[132:133]
	v_pk_fma_f32 v[246:247], v[138:139], v[246:247], v[134:135]
	v_pk_fma_f32 v[248:249], v[128:129], v[248:249], v[140:141]
	v_pk_fma_f32 v[250:251], v[130:131], v[250:251], v[142:143]
	v_pk_fma_f32 v[44:45], v[244:245], s[26:27], v[44:45] op_sel_hi:[1,0,1]
	v_pk_fma_f32 v[46:47], v[246:247], s[26:27], v[46:47] op_sel_hi:[1,0,1]
	v_pk_fma_f32 v[40:41], v[248:249], s[26:27], v[40:41] op_sel_hi:[1,0,1]
	v_pk_fma_f32 v[42:43], v[250:251], s[26:27], v[42:43] op_sel_hi:[1,0,1]
	global_store_dwordx4 v[218:219], v[44:47], off
	global_store_dwordx4 v[218:219], v[40:43], off offset:16
	v_lshl_add_u64 v[218:219], v[218:219], 0, s[98:99]
	global_load_dwordx2 v[242:243], v[168:169], off offset:1152
	global_load_dwordx4 v[244:247], v[216:217], off
	global_load_dwordx4 v[248:251], v[216:217], off offset:16
	v_lshl_add_u64 v[216:217], v[216:217], 0, s[98:99]
	s_waitcnt vmcnt(10)
	v_sub_f32_e32 v184, v184, v192
	v_sub_f32_e32 v185, v185, v192
	v_sub_f32_e32 v186, v186, v192
	v_sub_f32_e32 v187, v187, v192
	v_sub_f32_e32 v188, v188, v192
	v_sub_f32_e32 v189, v189, v192
	v_sub_f32_e32 v190, v190, v192
	v_sub_f32_e32 v191, v191, v192
	v_pk_mul_f32 v[184:185], v[192:193], v[184:185] op_sel:[1,0]
	v_pk_mul_f32 v[186:187], v[192:193], v[186:187] op_sel:[1,0]
	v_pk_mul_f32 v[188:189], v[192:193], v[188:189] op_sel:[1,0]
	v_pk_mul_f32 v[190:191], v[192:193], v[190:191] op_sel:[1,0]
	v_pk_fma_f32 v[184:185], v[136:137], v[184:185], v[132:133]
	v_pk_fma_f32 v[186:187], v[138:139], v[186:187], v[134:135]
	v_pk_fma_f32 v[188:189], v[128:129], v[188:189], v[140:141]
	v_pk_fma_f32 v[190:191], v[130:131], v[190:191], v[142:143]
	v_pk_fma_f32 v[36:37], v[184:185], s[26:27], v[36:37] op_sel_hi:[1,0,1]
	v_pk_fma_f32 v[38:39], v[186:187], s[26:27], v[38:39] op_sel_hi:[1,0,1]
	v_pk_fma_f32 v[32:33], v[188:189], s[26:27], v[32:33] op_sel_hi:[1,0,1]
	v_pk_fma_f32 v[34:35], v[190:191], s[26:27], v[34:35] op_sel_hi:[1,0,1]
	global_store_dwordx4 v[218:219], v[36:39], off
	global_store_dwordx4 v[218:219], v[32:35], off offset:16
	v_lshl_add_u64 v[218:219], v[218:219], 0, s[100:101]
	global_load_dwordx2 v[192:193], v[168:169], off offset:1280
	global_load_dwordx4 v[184:187], v[216:217], off
	global_load_dwordx4 v[188:191], v[216:217], off offset:16
	v_lshl_add_u64 v[216:217], v[216:217], 0, s[98:99]
	s_waitcnt vmcnt(10)
	v_sub_f32_e32 v232, v232, v240
	v_sub_f32_e32 v233, v233, v240
	v_sub_f32_e32 v234, v234, v240
	v_sub_f32_e32 v235, v235, v240
	v_sub_f32_e32 v236, v236, v240
	v_sub_f32_e32 v237, v237, v240
	v_sub_f32_e32 v238, v238, v240
	v_sub_f32_e32 v239, v239, v240
	v_pk_mul_f32 v[232:233], v[240:241], v[232:233] op_sel:[1,0]
	v_pk_mul_f32 v[234:235], v[240:241], v[234:235] op_sel:[1,0]
	v_pk_mul_f32 v[236:237], v[240:241], v[236:237] op_sel:[1,0]
	v_pk_mul_f32 v[238:239], v[240:241], v[238:239] op_sel:[1,0]
	v_pk_fma_f32 v[232:233], v[136:137], v[232:233], v[132:133]
	v_pk_fma_f32 v[234:235], v[138:139], v[234:235], v[134:135]
	v_pk_fma_f32 v[236:237], v[128:129], v[236:237], v[140:141]
	v_pk_fma_f32 v[238:239], v[130:131], v[238:239], v[142:143]
	v_pk_fma_f32 v[28:29], v[232:233], s[26:27], v[28:29] op_sel_hi:[1,0,1]
	v_pk_fma_f32 v[30:31], v[234:235], s[26:27], v[30:31] op_sel_hi:[1,0,1]
	v_pk_fma_f32 v[24:25], v[236:237], s[26:27], v[24:25] op_sel_hi:[1,0,1]
	v_pk_fma_f32 v[26:27], v[238:239], s[26:27], v[26:27] op_sel_hi:[1,0,1]
	global_store_dwordx4 v[218:219], v[28:31], off
	global_store_dwordx4 v[218:219], v[24:27], off offset:16
	v_lshl_add_u64 v[218:219], v[218:219], 0, s[98:99]
	global_load_dwordx2 v[240:241], v[168:169], off offset:1408
	global_load_dwordx4 v[232:235], v[216:217], off
	global_load_dwordx4 v[236:239], v[216:217], off offset:16
	s_waitcnt vmcnt(10)
;     __device__ __forceinline__ void operator()(const f32x4 (&acc)[2][2][4][2], const Unit& u, int wr, int wc, int fr, int fq) const {
;     ...
;                 for (int m = 0; m < 4; ++m) { const int row = row0 + ai * HALF + m * 16; const size_t p = (size_t)row * ldc + col0 + bj * HALF;
;                     const float mean = stats[2 * row], rstd = stats[2 * row + 1];
;                     const f32x4 r0 = *(const f32x4*)(res + p), r1 = *(const f32x4*)(res + p + 4);
;                     const f32x4 n0 = (r0 - mean) * rstd * g0 + b0, n1 = (r1 - mean) * rstd * g1 + b1;
;                     *(f32x4*)(out + p) = n0 * alpha + acc[ai][bj][m][0]; *(f32x4*)(out + p + 4) = n1 * alpha + acc[ai][bj][m][1]; }
	v_sub_f32_e32 v244, v244, v242
	v_sub_f32_e32 v245, v245, v242
	v_sub_f32_e32 v246, v246, v242
	v_sub_f32_e32 v247, v247, v242
	v_sub_f32_e32 v248, v248, v242
	v_sub_f32_e32 v249, v249, v242
	v_sub_f32_e32 v250, v250, v242
	v_sub_f32_e32 v251, v251, v242
	v_pk_mul_f32 v[244:245], v[242:243], v[244:245] op_sel:[1,0]
	v_pk_mul_f32 v[246:247], v[242:243], v[246:247] op_sel:[1,0]
	v_pk_mul_f32 v[248:249], v[242:243], v[248:249] op_sel:[1,0]
	v_pk_mul_f32 v[250:251], v[242:243], v[250:251] op_sel:[1,0]
	v_pk_fma_f32 v[244:245], v[136:137], v[244:245], v[132:133]
	v_pk_fma_f32 v[246:247], v[138:139], v[246:247], v[134:135]
	v_pk_fma_f32 v[248:249], v[128:129], v[248:249], v[140:141]
	v_pk_fma_f32 v[250:251], v[130:131], v[250:251], v[142:143]
	v_pk_fma_f32 v[20:21], v[244:245], s[26:27], v[20:21] op_sel_hi:[1,0,1]
	v_pk_fma_f32 v[22:23], v[246:247], s[26:27], v[22:23] op_sel_hi:[1,0,1]
	v_pk_fma_f32 v[16:17], v[248:249], s[26:27], v[16:17] op_sel_hi:[1,0,1]
	v_pk_fma_f32 v[18:19], v[250:251], s[26:27], v[18:19] op_sel_hi:[1,0,1]
	global_store_dwordx4 v[218:219], v[20:23], off
	global_store_dwordx4 v[218:219], v[16:19], off offset:16
	v_lshl_add_u64 v[218:219], v[218:219], 0, s[98:99]
	s_waitcnt vmcnt(7)
	v_sub_f32_e32 v184, v184, v192
	v_sub_f32_e32 v185, v185, v192
	v_sub_f32_e32 v186, v186, v192
	v_sub_f32_e32 v187, v187, v192
	v_sub_f32_e32 v188, v188, v192
	v_sub_f32_e32 v189, v189, v192
	v_sub_f32_e32 v190, v190, v192
	v_sub_f32_e32 v191, v191, v192
	v_pk_mul_f32 v[184:185], v[192:193], v[184:185] op_sel:[1,0]
	v_pk_mul_f32 v[186:187], v[192:193], v[186:187] op_sel:[1,0]
	v_pk_mul_f32 v[188:189], v[192:193], v[188:189] op_sel:[1,0]
	v_pk_mul_f32 v[190:191], v[192:193], v[190:191] op_sel:[1,0]
	v_pk_fma_f32 v[184:185], v[136:137], v[184:185], v[132:133]
	v_pk_fma_f32 v[186:187], v[138:139], v[186:187], v[134:135]
	v_pk_fma_f32 v[188:189], v[128:129], v[188:189], v[140:141]
	v_pk_fma_f32 v[190:191], v[130:131], v[190:191], v[142:143]
	v_pk_fma_f32 v[12:13], v[184:185], s[26:27], v[12:13] op_sel_hi:[1,0,1]
	v_pk_fma_f32 v[14:15], v[186:187], s[26:27], v[14:15] op_sel_hi:[1,0,1]
	v_pk_fma_f32 v[8:9], v[188:189], s[26:27], v[8:9] op_sel_hi:[1,0,1]
	v_pk_fma_f32 v[10:11], v[190:191], s[26:27], v[10:11] op_sel_hi:[1,0,1]
	global_store_dwordx4 v[218:219], v[12:15], off
	global_store_dwordx4 v[218:219], v[8:11], off offset:16
	v_lshl_add_u64 v[218:219], v[218:219], 0, s[98:99]
	s_waitcnt vmcnt(4)
	v_sub_f32_e32 v232, v232, v240
	v_sub_f32_e32 v233, v233, v240
	v_sub_f32_e32 v234, v234, v240
	v_sub_f32_e32 v235, v235, v240
	v_sub_f32_e32 v236, v236, v240
	v_sub_f32_e32 v237, v237, v240
	v_sub_f32_e32 v238, v238, v240
	v_sub_f32_e32 v239, v239, v240
	v_pk_mul_f32 v[232:233], v[240:241], v[232:233] op_sel:[1,0]
	v_pk_mul_f32 v[234:235], v[240:241], v[234:235] op_sel:[1,0]
	v_pk_mul_f32 v[236:237], v[240:241], v[236:237] op_sel:[1,0]
	v_pk_mul_f32 v[238:239], v[240:241], v[238:239] op_sel:[1,0]
	v_pk_fma_f32 v[232:233], v[136:137], v[232:233], v[132:133]
	v_pk_fma_f32 v[234:235], v[138:139], v[234:235], v[134:135]
	v_pk_fma_f32 v[236:237], v[128:129], v[236:237], v[140:141]
	v_pk_fma_f32 v[238:239], v[130:131], v[238:239], v[142:143]
	v_pk_fma_f32 v[4:5], v[232:233], s[26:27], v[4:5] op_sel_hi:[1,0,1]
	v_pk_fma_f32 v[6:7], v[234:235], s[26:27], v[6:7] op_sel_hi:[1,0,1]
	v_pk_fma_f32 v[0:1], v[236:237], s[26:27], v[0:1] op_sel_hi:[1,0,1]
	v_pk_fma_f32 v[2:3], v[238:239], s[26:27], v[2:3] op_sel_hi:[1,0,1]
	global_store_dwordx4 v[218:219], v[4:7], off
	global_store_dwordx4 v[218:219], v[0:3], off offset:16
	s_cbranch_vccnz .LBB0_1461
	s_andn2_b64 vcc, exec, s[6:7]
	s_cbranch_vccnz .LBB0_1460
	s_barrier
	s_branch .LBB0_1460
